# attention K/V LDS-DMA addressing: SGPR pass base + 32-bit lane offset (one v_add_u32 per piece instead of 64-bit VALU adds)
# speedup vs baseline: 1.0145x; 1.0145x over previous
; __device__ __forceinline__ float sum32x(float v) { auto rr = __builtin_amdgcn_permlane32_swap(__float_as_uint(v), __float_as_uint(v), false, false); return __uint_as_float(rr[0]) + __uint_as_float(rr[1]); }
; __device__ __forceinline__ float oload(LAS unsigned char* lds, int tid, int i) { return ((LAS float*)(lds + OSAVE_OFF) + tid)[i * 512]; }
; template <int DQK, int MODE> ...
;     ...
;     const float lt = sum32x(l_run);
;     linv = lt > 0.f ? 1.0f / lt : 0.f;
; __device__ __forceinline__ void attn_phase(LAS unsigned char* lds, int* counter, const bf16_t* __restrict__ P, const bf16_t* __restrict__ Qm, const bf16_t* __restrict__ Kmla, ...
;     ...
;             const float l2 = lam * linv; float ss = 0.f;
; #pragma unroll
;             for (int i = 0; i < 16; ++i) { o[0][i] = oload(lds, tid, i) - l2 * o[0][i]; o[1][i] = oload(lds, tid, 16 + i) - l2 * o[1][i]; ss += o[0][i] * o[0][i] + o[1][i] * o[1][i]; }
;             ss = sum32x(ss);
;             const float rs = (1.0f / sqrtf(ss * (1.0f / 64) + EPS)) * (1.0f - lam_init);
; #pragma unroll
;             for (int dh = 0; dh < 2; ++dh)
; #pragma unroll
;                 for (int a = 0; a < 4; ++a) { const f32x4 g4 = *(const f32x4*)(dng + 32 * dh + 8 * a + 4 * hi);
; #pragma unroll
;                     for (int j = 0; j < 4; ++j) o[dh][4 * a + j] *= rs * g4[j]; }
;             store_o_bf16(Omix + (size_t)(b * SEQ + tq) * DM + 256 + h * 64, o, hi);
.LBB0_667:
	v_readlane_b32 s86, v254, 37
	v_readlane_b32 s87, v254, 38
	v_mov_b32_e32 v32, v139
	s_nop 1
	v_permlane32_swap_b32_e32 v139, v32
	v_add_f32_e32 v32, v139, v32
	v_div_scale_f32 v33, s[2:3], v32, v32, 1.0
	v_rcp_f32_e32 v34, v33
	s_waitcnt vmcnt(0) lgkmcnt(0)
	s_barrier
	ds_read2st64_b32 v[54:55], v132 offset1:8
	ds_read2st64_b32 v[48:49], v132 offset0:128 offset1:136
	ds_read2st64_b32 v[56:57], v132 offset0:16 offset1:24
	ds_read2st64_b32 v[50:51], v132 offset0:144 offset1:152
	ds_read2st64_b32 v[58:59], v132 offset0:32 offset1:40
	ds_read2st64_b32 v[60:61], v132 offset0:160 offset1:168
	ds_read2st64_b32 v[62:63], v132 offset0:48 offset1:56
	ds_read2st64_b32 v[64:65], v132 offset0:176 offset1:184
	ds_read2st64_b32 v[66:67], v132 offset0:64 offset1:72
	ds_read2st64_b32 v[68:69], v132 offset0:192 offset1:200
	ds_read2st64_b32 v[70:71], v132 offset0:80 offset1:88
	ds_read2st64_b32 v[72:73], v132 offset0:208 offset1:216
	ds_read2st64_b32 v[74:75], v132 offset0:96 offset1:104
	ds_read2st64_b32 v[76:77], v132 offset0:224 offset1:232
	ds_read2st64_b32 v[78:79], v132 offset0:112 offset1:120
	ds_read2st64_b32 v[80:81], v132 offset0:240 offset1:248
	v_lshlrev_b32_e32 v82, 4, v190
	v_fma_f32 v35, -v33, v34, 1.0
	v_fmac_f32_e32 v34, v35, v34
	v_div_scale_f32 v35, vcc, 1.0, v32, 1.0
	v_mul_f32_e32 v36, v35, v34
	v_fma_f32 v37, -v33, v36, v35
	v_fmac_f32_e32 v36, v37, v34
	v_fma_f32 v33, -v33, v36, v35
	v_div_fmas_f32 v33, v33, v34, v36
	v_div_fixup_f32 v33, v33, v32, 1.0
	v_cmp_lt_f32_e32 vcc, 0, v32
	v_readfirstlane_b32 s2, v182
	v_readfirstlane_b32 s3, v183
	v_cndmask_b32_e32 v32, 0, v33, vcc
	v_mul_f32_e32 v52, v180, v32
	s_nop 2
	global_load_dwordx4 v[32:35], v82, s[2:3]
	global_load_dwordx4 v[36:39], v82, s[2:3] offset:32
	global_load_dwordx4 v[40:43], v82, s[2:3] offset:64
	global_load_dwordx4 v[44:47], v82, s[2:3] offset:96
	s_waitcnt lgkmcnt(0)
	v_pk_fma_f32 v[84:85], v[16:17], v[52:53], v[48:49] op_sel_hi:[1,0,1] neg_lo:[1,0,0] neg_hi:[1,0,0]
	v_pk_fma_f32 v[88:89], v[18:19], v[52:53], v[50:51] op_sel_hi:[1,0,1] neg_lo:[1,0,0] neg_hi:[1,0,0]
	global_load_dwordx4 v[16:19], v82, s[2:3] offset:128
	global_load_dwordx4 v[48:51], v82, s[2:3] offset:160
	v_pk_fma_f32 v[60:61], v[20:21], v[52:53], v[60:61] op_sel_hi:[1,0,1] neg_lo:[1,0,0] neg_hi:[1,0,0]
	v_pk_fma_f32 v[64:65], v[22:23], v[52:53], v[64:65] op_sel_hi:[1,0,1] neg_lo:[1,0,0] neg_hi:[1,0,0]
	v_pk_fma_f32 v[68:69], v[24:25], v[52:53], v[68:69] op_sel_hi:[1,0,1] neg_lo:[1,0,0] neg_hi:[1,0,0]
	v_pk_fma_f32 v[72:73], v[26:27], v[52:53], v[72:73] op_sel_hi:[1,0,1] neg_lo:[1,0,0] neg_hi:[1,0,0]
	global_load_dwordx4 v[20:23], v82, s[2:3] offset:192
	global_load_dwordx4 v[24:27], v82, s[2:3] offset:224
	v_pk_mul_f32 v[86:87], v[84:85], v[84:85]
	v_pk_fma_f32 v[0:1], v[0:1], v[52:53], v[54:55] op_sel_hi:[1,0,1] neg_lo:[1,0,0] neg_hi:[1,0,0]
	v_pk_mul_f32 v[90:91], v[88:89], v[88:89]
	v_pk_fma_f32 v[28:29], v[28:29], v[52:53], v[76:77] op_sel_hi:[1,0,1] neg_lo:[1,0,0] neg_hi:[1,0,0]
	v_pk_fma_f32 v[30:31], v[30:31], v[52:53], v[80:81] op_sel_hi:[1,0,1] neg_lo:[1,0,0] neg_hi:[1,0,0]
	v_pk_fma_f32 v[14:15], v[14:15], v[52:53], v[78:79] op_sel_hi:[1,0,1] neg_lo:[1,0,0] neg_hi:[1,0,0]
	v_pk_fma_f32 v[12:13], v[12:13], v[52:53], v[74:75] op_sel_hi:[1,0,1] neg_lo:[1,0,0] neg_hi:[1,0,0]
	v_pk_fma_f32 v[10:11], v[10:11], v[52:53], v[70:71] op_sel_hi:[1,0,1] neg_lo:[1,0,0] neg_hi:[1,0,0]
	v_pk_fma_f32 v[8:9], v[8:9], v[52:53], v[66:67] op_sel_hi:[1,0,1] neg_lo:[1,0,0] neg_hi:[1,0,0]
	v_pk_fma_f32 v[6:7], v[6:7], v[52:53], v[62:63] op_sel_hi:[1,0,1] neg_lo:[1,0,0] neg_hi:[1,0,0]
	v_pk_fma_f32 v[4:5], v[4:5], v[52:53], v[58:59] op_sel_hi:[1,0,1] neg_lo:[1,0,0] neg_hi:[1,0,0]
	v_pk_fma_f32 v[2:3], v[2:3], v[52:53], v[56:57] op_sel_hi:[1,0,1] neg_lo:[1,0,0] neg_hi:[1,0,0]
	v_pk_fma_f32 v[52:53], v[0:1], v[0:1], v[86:87]
	v_pk_fma_f32 v[56:57], v[2:3], v[2:3], v[90:91]
	v_pk_add_f32 v[52:53], v[52:53], v[52:53] op_sel:[0,1] op_sel_hi:[1,0]
	v_pk_mul_f32 v[92:93], v[60:61], v[60:61]
	v_pk_add_f32 v[52:53], v[56:57], v[52:53]
	v_pk_fma_f32 v[58:59], v[4:5], v[4:5], v[92:93]
	v_pk_add_f32 v[52:53], v[56:57], v[52:53] op_sel:[1,0] op_sel_hi:[0,1]
	v_pk_mul_f32 v[94:95], v[64:65], v[64:65]
	v_pk_add_f32 v[52:53], v[52:53], v[58:59]
	v_pk_fma_f32 v[62:63], v[6:7], v[6:7], v[94:95]
	v_pk_add_f32 v[52:53], v[52:53], v[58:59] op_sel:[0,1] op_sel_hi:[1,0]
	v_pk_mul_f32 v[96:97], v[68:69], v[68:69]
	v_pk_add_f32 v[52:53], v[52:53], v[62:63]
	v_pk_fma_f32 v[66:67], v[8:9], v[8:9], v[96:97]
	v_pk_add_f32 v[52:53], v[52:53], v[62:63] op_sel:[0,1] op_sel_hi:[1,0]
	v_pk_mul_f32 v[98:99], v[72:73], v[72:73]
	v_pk_add_f32 v[52:53], v[52:53], v[66:67]
	v_pk_fma_f32 v[70:71], v[10:11], v[10:11], v[98:99]
	v_pk_add_f32 v[52:53], v[52:53], v[66:67] op_sel:[0,1] op_sel_hi:[1,0]
	v_pk_mul_f32 v[76:77], v[28:29], v[28:29]
	v_pk_add_f32 v[52:53], v[52:53], v[70:71]
	v_pk_fma_f32 v[74:75], v[12:13], v[12:13], v[76:77]
	v_pk_add_f32 v[52:53], v[52:53], v[70:71] op_sel:[0,1] op_sel_hi:[1,0]
	v_pk_mul_f32 v[78:79], v[30:31], v[30:31]
	v_pk_add_f32 v[52:53], v[52:53], v[74:75]
	v_pk_fma_f32 v[78:79], v[14:15], v[14:15], v[78:79]
	v_pk_add_f32 v[52:53], v[52:53], v[74:75] op_sel:[0,1] op_sel_hi:[1,0]
	s_mov_b32 s2, 0xf800000
	v_pk_add_f32 v[52:53], v[52:53], v[78:79]
	s_lshl_b32 s80, s23, 1
	v_pk_add_f32 v[52:53], v[52:53], v[78:79] op_sel:[0,1] op_sel_hi:[1,0]
	v_mov_b32_e32 v83, v215
	v_mov_b32_e32 v53, v52
	s_nop 1
	v_permlane32_swap_b32_e32 v52, v53
	v_add_f32_e32 v52, v52, v53
	v_fmamk_f32 v52, v52, 0x3c800000, v244
	v_mul_f32_e32 v53, 0x4f800000, v52
	v_cmp_gt_f32_e32 vcc, s2, v52
	s_nop 1
	v_cndmask_b32_e32 v52, v52, v53, vcc
	v_sqrt_f32_e32 v53, v52
	s_nop 0
	v_add_u32_e32 v54, -1, v53
	v_fma_f32 v55, -v54, v53, v52
	v_cmp_ge_f32_e64 s[2:3], 0, v55
	v_add_u32_e32 v55, 1, v53
	s_nop 0
	v_cndmask_b32_e64 v54, v53, v54, s[2:3]
	v_fma_f32 v53, -v55, v53, v52
	v_cmp_lt_f32_e64 s[2:3], 0, v53
	s_nop 1
	v_cndmask_b32_e64 v53, v54, v55, s[2:3]
	v_mul_f32_e32 v54, 0x37800000, v53
	v_cndmask_b32_e32 v53, v53, v54, vcc
	v_cmp_class_f32_e32 vcc, v52, v245
	s_nop 1
	v_cndmask_b32_e32 v52, v53, v52, vcc
	v_div_scale_f32 v53, s[2:3], v52, v52, 1.0
	v_rcp_f32_e32 v54, v53
	v_readlane_b32 s2, v254, 46
	v_readlane_b32 s3, v254, 47
	v_fma_f32 v55, -v53, v54, 1.0
	v_fmac_f32_e32 v54, v55, v54
	v_div_scale_f32 v55, vcc, 1.0, v52, 1.0
	v_mul_f32_e32 v56, v55, v54
	v_fma_f32 v57, -v53, v56, v55
	v_fmac_f32_e32 v56, v57, v54
	v_fma_f32 v53, -v53, v56, v55
	v_div_fmas_f32 v53, v53, v54, v56
	v_div_fixup_f32 v52, v53, v52, 1.0
	v_mul_f32_e32 v52, v181, v52
	s_waitcnt vmcnt(0)
; __device__ __forceinline__ unsigned cvtpk(float lo, float hi) { f32x2 v = {lo, hi}; bf16x2_t b = __builtin_convertvector(v, bf16x2_t); return __builtin_bit_cast(unsigned, b); }
; __device__ __forceinline__ void store_o_bf16(bf16_t* dst, const f32x16 (&o)[2], int hi) {
; #pragma unroll
;     for (int dh = 0; dh < 2; ++dh)
; #pragma unroll
;         for (int ap = 0; ap < 2; ++ap) {
;             const int a0 = 2 * ap, a1 = a0 + 1;
;             unsigned x0 = cvtpk(o[dh][4 * a0], o[dh][4 * a0 + 1]), x1 = cvtpk(o[dh][4 * a0 + 2], o[dh][4 * a0 + 3]);
;             unsigned y0 = cvtpk(o[dh][4 * a1], o[dh][4 * a1 + 1]), y1 = cvtpk(o[dh][4 * a1 + 2], o[dh][4 * a1 + 3]);
;             const auto r0 = __builtin_amdgcn_permlane32_swap(x0, y0, false, false);
;             const auto r1 = __builtin_amdgcn_permlane32_swap(x1, y1, false, false);
;             const u32x4 w = {r0[0], r1[0], r0[1], r1[1]};
;             *(u32x4*)(dst + 32 * dh + 8 * (hi ? a1 : a0)) = w;
;         }
; }
; __device__ __forceinline__ void attn_phase(LAS unsigned char* lds, int* counter, const bf16_t* __restrict__ P, const bf16_t* __restrict__ Qm, const bf16_t* __restrict__ Kmla, ...
;     ...
; #pragma unroll
;             for (int dh = 0; dh < 2; ++dh)
; #pragma unroll
;                 for (int a = 0; a < 4; ++a) { const f32x4 g4 = *(const f32x4*)(dng + 32 * dh + 8 * a + 4 * hi);
; #pragma unroll
;                     for (int j = 0; j < 4; ++j) o[dh][4 * a + j] *= rs * g4[j]; }
;             store_o_bf16(Omix + (size_t)(b * SEQ + tq) * DM + 256 + h * 64, o, hi);
	v_pk_mul_f32 v[32:33], v[32:33], v[52:53] op_sel_hi:[1,0]
	v_pk_mul_f32 v[24:25], v[52:53], v[24:25] op_sel_hi:[0,1]
	v_pk_mul_f32 v[0:1], v[0:1], v[32:33]
	v_pk_mul_f32 v[32:33], v[34:35], v[52:53] op_sel_hi:[1,0]
	v_pk_mul_f32 v[24:25], v[28:29], v[24:25]
	v_pk_mul_f32 v[2:3], v[2:3], v[32:33]
	v_pk_mul_f32 v[32:33], v[36:37], v[52:53] op_sel_hi:[1,0]
	v_lshl_add_u32 v28, s22, 12, v214
	v_pk_mul_f32 v[4:5], v[4:5], v[32:33]
	v_pk_mul_f32 v[32:33], v[38:39], v[52:53] op_sel_hi:[1,0]
	v_ashrrev_i32_e32 v29, 31, v28
	v_pk_mul_f32 v[6:7], v[6:7], v[32:33]
	v_pk_mul_f32 v[32:33], v[40:41], v[52:53] op_sel_hi:[1,0]
	v_lshlrev_b64 v[28:29], 11, v[28:29]
	v_pk_mul_f32 v[8:9], v[8:9], v[32:33]
	v_pk_mul_f32 v[32:33], v[42:43], v[52:53] op_sel_hi:[1,0]
	v_lshl_add_u64 v[28:29], s[2:3], 0, v[28:29]
	v_pk_mul_f32 v[10:11], v[10:11], v[32:33]
	v_pk_mul_f32 v[32:33], v[44:45], v[52:53] op_sel_hi:[1,0]
	v_lshl_add_u64 v[28:29], v[28:29], 0, s[80:81]
	v_pk_mul_f32 v[12:13], v[12:13], v[32:33]
	v_pk_mul_f32 v[32:33], v[46:47], v[52:53] op_sel_hi:[1,0]
	v_cvt_pk_bf16_f32 v0, v0, v1
	v_cvt_pk_bf16_f32 v1, v2, v3
	v_cvt_pk_bf16_f32 v2, v4, v5
	v_cvt_pk_bf16_f32 v3, v6, v7
	v_pk_mul_f32 v[14:15], v[14:15], v[32:33]
	v_permlane32_swap_b32_e32 v0, v2
	v_permlane32_swap_b32_e32 v1, v3
	v_lshl_add_u64 v[4:5], v[28:29], 0, v[82:83]
	v_cmp_eq_u32_e32 vcc, 0, v190
	v_pk_mul_f32 v[16:17], v[16:17], v[52:53] op_sel_hi:[1,0]
	v_pk_mul_f32 v[18:19], v[18:19], v[52:53] op_sel_hi:[1,0]
	v_pk_mul_f32 v[32:33], v[48:49], v[52:53] op_sel_hi:[1,0]
	v_pk_mul_f32 v[34:35], v[50:51], v[52:53] op_sel_hi:[1,0]
	global_store_dwordx4 v[4:5], v[0:3], off offset:512
	v_cndmask_b32_e64 v214, 48, 32, vcc
	v_pk_mul_f32 v[16:17], v[84:85], v[16:17]
	v_cvt_pk_bf16_f32 v0, v8, v9
	v_cvt_pk_bf16_f32 v1, v10, v11
	v_cvt_pk_bf16_f32 v2, v12, v13
	v_cvt_pk_bf16_f32 v3, v14, v15
	v_pk_mul_f32 v[18:19], v[88:89], v[18:19]
	v_pk_mul_f32 v[32:33], v[60:61], v[32:33]
	v_pk_mul_f32 v[34:35], v[64:65], v[34:35]
	v_permlane32_swap_b32_e32 v0, v2
	v_permlane32_swap_b32_e32 v1, v3
	v_lshl_add_u64 v[6:7], v[28:29], 0, v[214:215]
	v_pk_mul_f32 v[20:21], v[52:53], v[20:21] op_sel_hi:[0,1]
	v_pk_mul_f32 v[22:23], v[52:53], v[22:23] op_sel_hi:[0,1]
	v_pk_mul_f32 v[26:27], v[52:53], v[26:27] op_sel_hi:[0,1]
	global_store_dwordx4 v[6:7], v[0:3], off offset:512
	v_pk_mul_f32 v[20:21], v[68:69], v[20:21]
	v_pk_mul_f32 v[22:23], v[72:73], v[22:23]
	v_cvt_pk_bf16_f32 v0, v16, v17
	v_cvt_pk_bf16_f32 v1, v18, v19
	v_cvt_pk_bf16_f32 v2, v32, v33
	v_cvt_pk_bf16_f32 v3, v34, v35
	v_pk_mul_f32 v[26:27], v[30:31], v[26:27]
	v_permlane32_swap_b32_e32 v0, v2
	v_permlane32_swap_b32_e32 v1, v3
	global_store_dwordx4 v[4:5], v[0:3], off offset:576
	s_nop 1
	v_cvt_pk_bf16_f32 v0, v20, v21
	v_cvt_pk_bf16_f32 v1, v22, v23
	v_cvt_pk_bf16_f32 v2, v24, v25
	v_cvt_pk_bf16_f32 v3, v26, v27
	s_nop 0
	v_permlane32_swap_b32_e32 v0, v2
	v_permlane32_swap_b32_e32 v1, v3
	global_store_dwordx4 v[6:7], v[0:3], off offset:576

; __device__ __forceinline__ int make_tid(int wave0) { int t = wave0 * 64 + (int)__builtin_amdgcn_mbcnt_hi(~0u, __builtin_amdgcn_mbcnt_lo(~0u, 0u)); asm volatile("" : "+v"(t)); return t; }
; #define AT_DMAV(t) do { const int t_ = AT_CL(t); LAS unsigned char* d_ = lds + (t_ % 3) * SLOT + KSL; \
;         __builtin_amdgcn_global_load_lds((const GAS unsigned*)(vsrc + (size_t)t_ * 64 * vs), (LAS unsigned*)(d_ + wid * 1024), 16, 0, 0); } while (0)
; template <int DQK, int MODE> ...
;     ...
;     const int tid = make_tid(wave0), lane = tid & 63, r32 = lane & 31, hi = lane >> 5;
;     const int wid = wave0;
;     const int tw0 = t0 + 32 * wid, tq = tw0 + r32;
;     bf16x8 qf[NDS];
; #pragma unroll
;     for (int ds = 0; ds < NDS; ++ds) qf[ds] = *(const bf16x8*)(Qp + (size_t)tq * qs + 16 * ds + 8 * hi);
;     int kt_lo = 0; const int kt_hi = (t0 >> 6) + 3;
;     if (MODE == 1) { const int lo = t0 - 511; kt_lo = lo > 0 ? (lo >> 6) : 0; }
;     unsigned long long selm = 0ull; if (MODE == 2) selm = selp[tq];
;     const int kc0 = wid % CPR, kc1 = (8 + (wid & 3)) % CPR;
;     const bf16_t* ksrc0 = Kp + (size_t)lane * ks + kc0 * 8;
;     const bf16_t* ksrc1 = Kp + (size_t)lane * ks + kc1 * 8;
;     const bf16_t* vsrc = Vp + (size_t)(16 * (wid & 3) + (lane >> 2)) * vs + (wid >> 2) * 32 + (lane & 3) * 8;
;     ...
;     o[0] = f32x16{}; o[1] = f32x16{};
;     float m_run = 0.f, l_run = 0.f; bool init = false;
;     f32x16 negm = f32x16{}; asm volatile("" : "+v"(negm));
;     f32x16 pa0 = f32x16{}, pa1 = f32x16{}, pb0 = f32x16{}, pb1 = f32x16{};
;     bf16x8 kf[2 * NDS];
;     AT_DMAK(kt_lo); AT_DMAV(kt_lo); AT_DMAK(kt_lo + 1); AT_DMAK(kt_lo + 2); AT_DMAV(kt_lo + 1);
;     if (NKW > 1) AT_WAITBAR(3); else AT_WAITBAR(2);
;     { AT_KFRAG(kt_lo); asm volatile("s_waitcnt lgkmcnt(0)\n\ts_barrier" ::: "memory");
;       const float b_ = AT_BIAS(kt_lo); AT_QKM(pa0, pa1, AT_SPLAT(b_)); }
; __device__ __forceinline__ void attn_phase(LAS unsigned char* lds, int* counter, const bf16_t* __restrict__ P, const bf16_t* __restrict__ Qm, const bf16_t* __restrict__ Kmla, ...
;     ...
;             const int b = (r - 64) >> 3, head = (r - 64) & 7, g = head >> 2;
;             const bf16_t* Pb = P + (size_t)b * SEQ * NPJ;
;             attn_pass<64, 2>(lds, Pb + C_NQ + head * 64, NPJ, Pb + C_NKV + 256 + g * 64, NPJ, Pb + C_NKV + 384 + g * 64, NPJ, t0, mask + (size_t)(b * 2 + g) * SEQ, o, linv, wave0);
.LBB0_683:
	s_not_b32 s2, s5
	s_lshl_b32 s2, s2, 8
	s_and_b32 s40, s2, 0xf00
	s_add_i32 s39, s40, s55
	v_bfe_u32 v190, v191, 5, 1
	v_and_or_b32 v214, v191, 31, s39
	s_cmp_gt_i32 s41, 31
	s_mov_b64 s[2:3], -1
	s_cbranch_scc0 .LBB0_728
	s_cmp_gt_u32 s41, 63
	s_cbranch_scc0 .LBB0_713
	s_sub_i32 s2, s41, 64
	s_lshr_b32 s22, s2, 3
	s_and_b32 s47, s41, 7
	s_bfe_u32 s4, s41, 0x10002
	s_mul_i32 s3, s22, 0x1400000
	v_readlane_b32 s6, v254, 48
	s_mul_hi_u32 s2, s22, 0x1400000
	v_readlane_b32 s7, v254, 49
	s_add_u32 s45, s6, s3
	s_addc_u32 s44, s7, s2
	s_lshl_b32 s42, s47, 6
	s_lshl_b32 s2, s47, 7
	s_add_u32 s16, s45, s2
	s_addc_u32 s17, s44, 0
	s_lshl_b32 s46, s4, 6
	s_lshl_b32 s2, s4, 7
	s_add_u32 s2, s45, s2
	s_addc_u32 s3, s44, 0
	s_lshl_b32 s5, s22, 1
	s_or_b32 s80, s5, s4
	s_lshl_b64 s[4:5], s[80:81], 15
	v_mov_b32_e32 v20, v246
	s_add_u32 s4, s34, s4
	s_addc_u32 s5, s35, s5
	v_and_b32_e32 v21, 31, v20
	v_or_b32_e32 v0, s39, v21
	v_mov_b32_e32 v1, v215
	v_lshl_add_u64 v[2:3], v[0:1], 3, s[4:5]
	global_load_dwordx2 v[144:145], v[2:3], off
	v_bfe_u32 v22, v20, 5, 1
	v_mov_b64_e32 v[2:3], s[16:17]
	v_mad_u64_u32 v[0:1], s[4:5], v0, s65, v[2:3]
	v_lshlrev_b32_e32 v2, 4, v22
	v_mov_b32_e32 v3, v215
	v_lshl_add_u64 v[0:1], v[0:1], 0, v[2:3]
	global_load_dwordx4 v[96:99], v[0:1], off offset:2368
	global_load_dwordx4 v[100:103], v[0:1], off offset:2400
	global_load_dwordx4 v[104:107], v[0:1], off offset:2432
	global_load_dwordx4 v[108:111], v[0:1], off offset:2464
	v_and_b32_e32 v4, 63, v20
	v_mul_u32_u24_e32 v0, 0xa00, v4
	v_lshlrev_b32_e32 v0, 1, v0
	v_mov_b32_e32 v1, v215
	v_lshl_add_u64 v[0:1], s[2:3], 0, v[0:1]
	s_lshl_b32 s18, s58, 1
	s_mov_b32 s19, s81
	v_lshl_add_u64 v[146:147], v[0:1], 0, s[18:19]
	v_bfe_u32 v0, v20, 2, 4
	v_or_b32_e32 v0, s59, v0
	v_mul_u32_u24_e32 v0, 0xa00, v0
	v_lshlrev_b32_e32 v0, 1, v0
	v_mov_b32_e32 v1, v215
	v_lshlrev_b32_e32 v2, 3, v20
	v_lshl_add_u64 v[0:1], s[2:3], 0, v[0:1]
	s_lshl_b32 s20, s60, 1
	s_mov_b32 s21, s81
	v_and_b32_e32 v23, 24, v2
	s_mov_b64 s[4:5], 0xf40
	v_lshl_add_u64 v[0:1], v[0:1], 0, s[20:21]
	v_lshlrev_b32_e32 v2, 1, v23
	s_mov_b32 m0, s61
	v_lshl_add_u64 v[16:17], v[146:147], 0, s[4:5]
	v_lshl_add_u64 v[18:19], v[0:1], 0, v[2:3]
	s_mov_b64 s[2:3], 0x1040
	v_mov_b32_e32 v0, v215
	v_mov_b32_e32 v1, v215
	v_mov_b32_e32 v2, v215
	v_mov_b32_e32 v4, v215
	v_mov_b32_e32 v5, v215
	v_mov_b32_e32 v6, v215
	v_mov_b32_e32 v7, v215
	v_mov_b32_e32 v8, v215
	v_mov_b32_e32 v9, v215
	v_mov_b32_e32 v10, v215
	v_mov_b32_e32 v11, v215
	v_mov_b32_e32 v12, v215
	v_mov_b32_e32 v13, v215
	v_mov_b32_e32 v14, v215
	v_mov_b32_e32 v15, v215
	v_lshl_add_u64 v[148:149], v[18:19], 0, s[2:3]
	global_load_lds_dwordx4 v[16:17], off
	s_mov_b32 m0, s82
	s_mov_b64 s[2:3], 0x50f40
	global_load_lds_dwordx4 v[148:149], off
	v_lshl_add_u64 v[0:1], v[146:147], 0, s[2:3]
	s_mov_b32 m0, s69
	s_mov_b64 s[2:3], 0xa0f40
	global_load_lds_dwordx4 v[0:1], off
	v_lshl_add_u64 v[0:1], v[146:147], 0, s[2:3]
	s_mov_b32 m0, s68
	s_mov_b64 s[2:3], 0x51040
	global_load_lds_dwordx4 v[0:1], off
	v_lshl_add_u64 v[0:1], v[18:19], 0, s[2:3]
	s_mov_b32 m0, s83
	v_lshlrev_b32_e32 v151, 10, v22
	global_load_lds_dwordx4 v[0:1], off
	v_lshlrev_b32_e32 v152, 4, v21
	s_waitcnt vmcnt(2) lgkmcnt(0)
	s_barrier
	v_add3_u32 v153, 0, v151, v152
	ds_read_b128 v[0:3], v153
	ds_read_b128 v[4:7], v153 offset:512
	v_mov_b32_e32 v9, v215
	s_lshr_b32 s2, s40, 6
	v_mov_b32_e32 v154, 0
	s_mov_b32 s23, s81
	s_waitcnt vmcnt(2)
	v_and_b32_e32 v8, 1, v144
	v_cmp_eq_u64_e32 vcc, 0, v[8:9]
	s_mov_b32 s19, 1
	s_mov_b32 s21, 4
	v_cndmask_b32_e32 v32, 0, v249, vcc
	v_mov_b32_e32 v33, v32
	v_mov_b32_e32 v34, v32
	v_mov_b32_e32 v35, v32
	v_mov_b32_e32 v36, v32
	v_mov_b32_e32 v37, v32
	v_mov_b32_e32 v38, v32
	v_mov_b32_e32 v39, v32
	v_mov_b32_e32 v40, v32
	v_mov_b32_e32 v41, v32
	v_mov_b32_e32 v42, v32
	v_mov_b32_e32 v43, v32
	v_mov_b32_e32 v44, v32
	v_mov_b32_e32 v45, v32
	v_mov_b32_e32 v46, v32
	v_mov_b32_e32 v47, v32
	s_mov_b32 s48, 0
	s_or_b32 s43, s2, 3
	s_waitcnt lgkmcnt(0)
	v_mfma_f32_32x32x16_bf16 v[48:63], v[0:3], v[96:99], v[32:47]
	s_mov_b64 s[2:3], 0
	s_movk_i32 s49, 0x7f
	v_mov_b32_e32 v150, 0
	v_mov_b32_e32 v8, v154
	v_mov_b32_e32 v9, v154
	v_mov_b32_e32 v10, v154
	v_mov_b32_e32 v11, v154
	v_mfma_f32_32x32x16_bf16 v[32:47], v[4:7], v[96:99], v[32:47]
	ds_read_b128 v[0:3], v153 offset:2048
	ds_read_b128 v[4:7], v153 offset:2560
	v_mov_b32_e32 v12, v154
	v_mov_b32_e32 v13, v154
	v_mov_b32_e32 v14, v154
	v_mov_b32_e32 v15, v154
	v_mov_b32_e32 v16, v154
	v_mov_b32_e32 v17, v154
	s_waitcnt lgkmcnt(1)
	v_mfma_f32_32x32x16_bf16 v[48:63], v[0:3], v[100:103], v[48:63]
	v_mov_b32_e32 v18, v154
	v_mov_b32_e32 v19, v154
	v_mov_b32_e32 v24, v154
	v_mov_b32_e32 v25, v154
	v_mov_b32_e32 v26, v154
	v_mov_b32_e32 v27, v154
	v_mov_b32_e32 v28, v154
	s_waitcnt lgkmcnt(0)
	v_mfma_f32_32x32x16_bf16 v[32:47], v[4:7], v[100:103], v[32:47]
	ds_read_b128 v[0:3], v153 offset:4096
	ds_read_b128 v[4:7], v153 offset:4608
	v_mov_b32_e32 v29, v154
	v_mov_b32_e32 v30, v154
	v_mov_b32_e32 v31, v154
	s_waitcnt lgkmcnt(1)
	v_mfma_f32_32x32x16_bf16 v[48:63], v[0:3], v[104:107], v[48:63]
	s_waitcnt lgkmcnt(0)
	v_mfma_f32_32x32x16_bf16 v[32:47], v[4:7], v[104:107], v[32:47]
	ds_read_b128 v[0:3], v153 offset:6144
	ds_read_b128 v[4:7], v153 offset:6656
	s_waitcnt lgkmcnt(0)
	s_barrier
	s_waitcnt lgkmcnt(1)
	v_mfma_f32_32x32x16_bf16 v[48:63], v[0:3], v[108:111], v[48:63]
	v_lshlrev_b32_e32 v2, 4, v20
	v_lshlrev_b32_e32 v0, 1, v20
	v_and_b32_e32 v2, 0xc0, v2
	v_and_b32_e32 v0, 32, v0
	v_lshl_or_b32 v2, v22, 8, v2
	v_or3_b32 v0, v2, v0, v23
	v_lshlrev_b32_e32 v1, 2, v22
	s_waitcnt lgkmcnt(0)
	v_mfma_f32_32x32x16_bf16 v[32:47], v[4:7], v[108:111], v[32:47]
	v_add_u32_e32 v155, 0, v0
	v_add_u32_e32 v0, s39, v21
	v_sub_u32_e32 v156, v0, v1
	v_mov_b32_e32 v0, 0
	v_mov_b32_e32 v1, v154
	v_mov_b32_e32 v2, v154
	v_mov_b32_e32 v3, v154
	v_mov_b32_e32 v4, v154
	v_mov_b32_e32 v5, v154
	v_mov_b32_e32 v6, v154
	v_mov_b32_e32 v7, v154
	v_mov_b32_e32 v20, v154
	v_mov_b32_e32 v21, v154
	v_mov_b32_e32 v22, v154
	v_mov_b32_e32 v23, v154
	v_readfirstlane_b32 s86, v146
	v_readfirstlane_b32 s87, v147
	v_readfirstlane_b32 s98, v148
	v_readfirstlane_b32 s99, v149
	s_nop 1
	v_subrev_u32_e32 v200, s86, v146
	v_subrev_u32_e32 v202, s98, v148
	s_add_u32 s86, s86, 0xf40
	s_addc_u32 s87, s87, 0
	s_branch .LBB0_689

.LBB0_689:
	s_add_i32 s4, s21, -1
	s_min_u32 s4, s4, s43
	s_mul_hi_u32 s5, s4, 0x55555556
	s_mul_i32 s5, s5, 3
	s_sub_i32 s5, s4, s5
	s_mul_i32 s4, s4, 0x28000
	s_lshl_b32 s5, s5, 14
	s_lshl_b32 s80, s4, 1
	s_add_i32 s50, s21, -2
	s_add_i32 s53, s5, 0
	v_add_u32_e32 v64, s80, v200
	s_mov_b64 s[4:5], 0xf40
	s_min_u32 s51, s50, s43
	s_mul_hi_u32 s4, s51, 0x55555556
	s_mul_i32 s4, s4, 3
	s_sub_i32 s4, s51, s4
	s_lshl_b32 s4, s4, 14
	s_add_i32 m0, s53, s89
	s_add_i32 s52, s4, 0
	s_mul_i32 s4, s51, 0x50000
	s_mov_b32 s5, s81
	global_load_lds_dwordx4 v64, s[86:87]
	v_add_u32_e32 v64, s4, v202
	s_add_i32 s4, s52, s95
	s_add_i32 m0, s4, 0x2000
	s_sub_i32 s4, s49, 64
	global_load_lds_dwordx4 v64, s[98:99]
	s_cmp_le_u32 s4, s39
	s_sub_i32 s5, s4, 94
	s_cmp_gt_i32 s5, s39
	s_cbranch_scc1 .Ltsk689_d1
	s_cmp_le_u32 s4, s39
	s_cbranch_scc1 .LBB0_691
	v_cmp_lt_i32_e64 s[4:5], -1, v156
	v_cmp_lt_i32_e64 s[6:7], 31, v156
	v_cmp_lt_i32_e32 vcc, 0, v156
	v_cndmask_b32_e64 v48, v249, v48, s[4:5]
	v_cmp_lt_i32_e64 s[4:5], 32, v156
	v_cndmask_b32_e64 v32, v249, v32, s[6:7]
	v_cmp_lt_i32_e64 s[6:7], 1, v156
	v_cndmask_b32_e32 v49, v249, v49, vcc
	v_cmp_lt_i32_e32 vcc, 33, v156
	v_cndmask_b32_e64 v33, v249, v33, s[4:5]
	v_cmp_lt_i32_e64 s[4:5], 2, v156
	v_cndmask_b32_e64 v50, v249, v50, s[6:7]
	v_cmp_lt_i32_e64 s[6:7], 34, v156
	v_cndmask_b32_e32 v34, v249, v34, vcc
	v_cmp_lt_i32_e32 vcc, 7, v156
	v_cndmask_b32_e64 v51, v249, v51, s[4:5]
	v_cmp_lt_i32_e64 s[4:5], 39, v156
	v_cndmask_b32_e64 v35, v249, v35, s[6:7]
	v_cmp_lt_i32_e64 s[6:7], 8, v156
	v_cndmask_b32_e32 v52, v249, v52, vcc
	v_cmp_lt_i32_e32 vcc, 40, v156
	v_cndmask_b32_e64 v36, v249, v36, s[4:5]
	v_cmp_lt_i32_e64 s[4:5], 9, v156
	v_cndmask_b32_e64 v53, v249, v53, s[6:7]
	v_cmp_lt_i32_e64 s[6:7], 41, v156
	v_cndmask_b32_e32 v37, v249, v37, vcc
	v_cmp_lt_i32_e32 vcc, 10, v156
	v_cndmask_b32_e64 v54, v249, v54, s[4:5]
	v_cmp_lt_i32_e64 s[4:5], 42, v156
	v_cndmask_b32_e64 v38, v249, v38, s[6:7]
	v_cmp_lt_i32_e64 s[6:7], 15, v156
	v_cndmask_b32_e32 v55, v249, v55, vcc
	v_cmp_lt_i32_e32 vcc, 47, v156
	v_cndmask_b32_e64 v39, v249, v39, s[4:5]
	v_cmp_lt_i32_e64 s[4:5], 16, v156
	v_cndmask_b32_e64 v56, v249, v56, s[6:7]
	v_cmp_lt_i32_e64 s[6:7], 48, v156
	v_cndmask_b32_e32 v40, v249, v40, vcc
	v_cmp_lt_i32_e32 vcc, 17, v156
	v_cndmask_b32_e64 v57, v249, v57, s[4:5]
	v_cmp_lt_i32_e64 s[4:5], 49, v156
	v_cndmask_b32_e64 v41, v249, v41, s[6:7]
	v_cmp_lt_i32_e64 s[6:7], 18, v156
	v_cndmask_b32_e32 v58, v249, v58, vcc
	v_cmp_lt_i32_e32 vcc, 50, v156
	v_cndmask_b32_e64 v42, v249, v42, s[4:5]
	v_cmp_lt_i32_e64 s[4:5], 23, v156
	v_cndmask_b32_e64 v59, v249, v59, s[6:7]
	v_cmp_lt_i32_e64 s[6:7], 55, v156
	v_cndmask_b32_e32 v43, v249, v43, vcc
	v_cmp_lt_i32_e32 vcc, 24, v156
	v_cndmask_b32_e64 v60, v249, v60, s[4:5]
	v_cmp_lt_i32_e64 s[4:5], 56, v156
	v_cndmask_b32_e64 v44, v249, v44, s[6:7]
	v_cmp_lt_i32_e64 s[6:7], 25, v156
	v_cndmask_b32_e32 v61, v249, v61, vcc
	v_cmp_lt_i32_e32 vcc, 57, v156
	v_cndmask_b32_e64 v45, v249, v45, s[4:5]
	v_cmp_lt_i32_e64 s[4:5], 26, v156
	v_cndmask_b32_e64 v62, v249, v62, s[6:7]
	v_cmp_lt_i32_e64 s[6:7], 58, v156
	v_cndmask_b32_e32 v46, v249, v46, vcc
	s_nop 0
	v_cndmask_b32_e64 v63, v249, v63, s[4:5]
	s_nop 0
	v_cndmask_b32_e64 v47, v249, v47, s[6:7]

.Ltsk689_s2:
	s_min_u32 s4, s21, s43
	s_mul_hi_u32 s5, s4, 0x55555556
	s_mul_i32 s5, s5, 3
	s_sub_i32 s5, s4, s5
	s_lshl_b32 s6, s5, 14
	s_mul_i32 s4, s4, 0x50000
	s_mov_b32 s5, s81
	v_add_u32_e32 v32, s4, v200
	s_mov_b64 s[4:5], 0xf40
	s_add_i32 m0, s61, s6
	s_add_i32 s4, s53, s95
	global_load_lds_dwordx4 v32, s[86:87]
	v_add_u32_e32 v32, s80, v202
	s_add_i32 m0, s4, 0x2000
	s_cmp_le_u32 s49, s39
	global_load_lds_dwordx4 v32, s[98:99]
	s_sub_i32 s5, s49, 94
	s_cmp_gt_i32 s5, s39
	s_cbranch_scc1 .Ltsk689_d2
	s_cmp_le_u32 s49, s39
	s_cbranch_scc1 .LBB0_696
	v_subrev_u32_e32 v32, 64, v156
	v_cmp_lt_i32_e64 s[4:5], -1, v32
	v_cmp_lt_i32_e64 s[6:7], 31, v32
	v_cmp_lt_i32_e32 vcc, 0, v32
	v_cndmask_b32_e64 v80, v249, v80, s[4:5]
	v_cmp_lt_i32_e64 s[4:5], 32, v32
	v_cndmask_b32_e64 v64, v249, v64, s[6:7]
	v_cmp_lt_i32_e64 s[6:7], 1, v32
	v_cndmask_b32_e32 v81, v249, v81, vcc
	v_cmp_lt_i32_e32 vcc, 33, v32
	v_cndmask_b32_e64 v65, v249, v65, s[4:5]
	v_cmp_lt_i32_e64 s[4:5], 2, v32
	v_cndmask_b32_e64 v82, v249, v82, s[6:7]
	v_cmp_lt_i32_e64 s[6:7], 34, v32
	v_cndmask_b32_e32 v66, v249, v66, vcc
	v_cmp_lt_i32_e32 vcc, 7, v32
	v_cndmask_b32_e64 v83, v249, v83, s[4:5]
	v_cmp_lt_i32_e64 s[4:5], 39, v32
	v_cndmask_b32_e64 v67, v249, v67, s[6:7]
	v_cmp_lt_i32_e64 s[6:7], 8, v32
	v_cndmask_b32_e32 v84, v249, v84, vcc
	v_cmp_lt_i32_e32 vcc, 40, v32
	v_cndmask_b32_e64 v68, v249, v68, s[4:5]
	v_cmp_lt_i32_e64 s[4:5], 9, v32
	v_cndmask_b32_e64 v85, v249, v85, s[6:7]
	v_cmp_lt_i32_e64 s[6:7], 41, v32
	v_cndmask_b32_e32 v69, v249, v69, vcc
	v_cmp_lt_i32_e32 vcc, 10, v32
	v_cndmask_b32_e64 v86, v249, v86, s[4:5]
	v_cmp_lt_i32_e64 s[4:5], 42, v32
	v_cndmask_b32_e64 v70, v249, v70, s[6:7]
	v_cmp_lt_i32_e64 s[6:7], 15, v32
	v_cndmask_b32_e32 v87, v249, v87, vcc
	v_cmp_lt_i32_e32 vcc, 47, v32
	v_cndmask_b32_e64 v71, v249, v71, s[4:5]
	v_cmp_lt_i32_e64 s[4:5], 16, v32
	v_cndmask_b32_e64 v88, v249, v88, s[6:7]
	v_cmp_lt_i32_e64 s[6:7], 48, v32
	v_cndmask_b32_e32 v72, v249, v72, vcc
	v_cmp_lt_i32_e32 vcc, 17, v32
	v_cndmask_b32_e64 v89, v249, v89, s[4:5]
	v_cmp_lt_i32_e64 s[4:5], 49, v32
	v_cndmask_b32_e64 v73, v249, v73, s[6:7]
	v_cmp_lt_i32_e64 s[6:7], 18, v32
	v_cndmask_b32_e32 v90, v249, v90, vcc
	v_cmp_lt_i32_e32 vcc, 50, v32
	v_cndmask_b32_e64 v74, v249, v74, s[4:5]
	v_cmp_lt_i32_e64 s[4:5], 23, v32
	v_cndmask_b32_e64 v91, v249, v91, s[6:7]
	v_cmp_lt_i32_e64 s[6:7], 55, v32
	v_cndmask_b32_e32 v75, v249, v75, vcc
	v_cmp_lt_i32_e32 vcc, 24, v32
	v_cndmask_b32_e64 v92, v249, v92, s[4:5]
	v_cmp_lt_i32_e64 s[4:5], 56, v32
	v_cndmask_b32_e64 v76, v249, v76, s[6:7]
	v_cmp_lt_i32_e64 s[6:7], 25, v32
	v_cndmask_b32_e32 v93, v249, v93, vcc
	v_cmp_lt_i32_e32 vcc, 57, v32
	v_cndmask_b32_e64 v77, v249, v77, s[4:5]
	v_cmp_lt_i32_e64 s[4:5], 26, v32
	v_cndmask_b32_e64 v94, v249, v94, s[6:7]
	v_cmp_lt_i32_e64 s[6:7], 58, v32
	v_cndmask_b32_e32 v78, v249, v78, vcc
	s_nop 0
	v_cndmask_b32_e64 v95, v249, v95, s[4:5]
	s_nop 0
	v_cndmask_b32_e64 v79, v249, v79, s[6:7]

; __device__ __forceinline__ int make_tid(int wave0) { int t = wave0 * 64 + (int)__builtin_amdgcn_mbcnt_hi(~0u, __builtin_amdgcn_mbcnt_lo(~0u, 0u)); asm volatile("" : "+v"(t)); return t; }
; #define AT_DMAV(t) do { const int t_ = AT_CL(t); LAS unsigned char* d_ = lds + (t_ % 3) * SLOT + KSL; \
;         __builtin_amdgcn_global_load_lds((const GAS unsigned*)(vsrc + (size_t)t_ * 64 * vs), (LAS unsigned*)(d_ + wid * 1024), 16, 0, 0); } while (0)
; #define AT_WAITBAR(N) asm volatile("s_waitcnt vmcnt(" #N ") lgkmcnt(0)\n\ts_barrier" ::: "memory")
; template <int DQK, int MODE> ...
;     ...
;     const int tid = make_tid(wave0), lane = tid & 63, r32 = lane & 31, hi = lane >> 5;
;     const int wid = wave0;
;     const int tw0 = t0 + 32 * wid, tq = tw0 + r32;
;     bf16x8 qf[NDS];
; #pragma unroll
;     for (int ds = 0; ds < NDS; ++ds) qf[ds] = *(const bf16x8*)(Qp + (size_t)tq * qs + 16 * ds + 8 * hi);
;     int kt_lo = 0; const int kt_hi = (t0 >> 6) + 3;
;     if (MODE == 1) { const int lo = t0 - 511; kt_lo = lo > 0 ? (lo >> 6) : 0; }
;     unsigned long long selm = 0ull; if (MODE == 2) selm = selp[tq];
;     const int kc0 = wid % CPR, kc1 = (8 + (wid & 3)) % CPR;
;     const bf16_t* ksrc0 = Kp + (size_t)lane * ks + kc0 * 8;
;     const bf16_t* ksrc1 = Kp + (size_t)lane * ks + kc1 * 8;
;     const bf16_t* vsrc = Vp + (size_t)(16 * (wid & 3) + (lane >> 2)) * vs + (wid >> 2) * 32 + (lane & 3) * 8;
;     ...
;     o[0] = f32x16{}; o[1] = f32x16{};
;     float m_run = 0.f, l_run = 0.f; bool init = false;
;     f32x16 negm = f32x16{}; asm volatile("" : "+v"(negm));
;     f32x16 pa0 = f32x16{}, pa1 = f32x16{}, pb0 = f32x16{}, pb1 = f32x16{};
;     bf16x8 kf[2 * NDS];
;     AT_DMAK(kt_lo); AT_DMAV(kt_lo); AT_DMAK(kt_lo + 1); AT_DMAK(kt_lo + 2); AT_DMAV(kt_lo + 1);
;     if (NKW > 1) AT_WAITBAR(3); else AT_WAITBAR(2);
; __device__ __forceinline__ void attn_phase(LAS unsigned char* lds, int* counter, const bf16_t* __restrict__ P, const bf16_t* __restrict__ Qm, const bf16_t* __restrict__ Kmla, ...
;     ...
;             const size_t row = (size_t)b * SEQ + tq;
;             osave(lds, tid, o, linv * gates[row * 24 + head * 3 + 1]);
;             attn_pass<64, 1>(lds, Pb + C_NQ + head * 64, NPJ, Pb + C_NKV + 512 + g * 64, NPJ, Pb + C_NKV + 640 + g * 64, NPJ, t0, nullptr, o, linv, wave0);
.LBB0_698:
	v_readlane_b32 s86, v254, 37
	v_readlane_b32 s87, v254, 38
	s_lshl_b64 s[2:3], s[22:23], 12
	v_lshl_add_u64 v[156:157], s[2:3], 0, v[214:215]
	s_nop 1
	v_mov_b64_e32 v[32:33], s[10:11]
	v_mad_u64_u32 v[32:33], s[2:3], v156, s85, v[32:33]
	v_mad_u32_u24 v33, v157, s85, v33
	s_mul_i32 s80, s47, 12
	s_waitcnt vmcnt(0) lgkmcnt(0)
	s_barrier
	v_lshl_add_u64 v[158:159], v[32:33], 0, s[80:81]
	global_load_dword v32, v[158:159], off offset:4
	v_mov_b32_e32 v33, v150
	s_nop 1
	v_permlane32_swap_b32_e32 v150, v33
	v_lshl_add_u32 v34, v191, 2, 0
	s_lshl_b32 s2, s46, 1
	v_add_f32_e32 v33, v150, v33
	v_add_u32_e32 v164, 0x10000, v34
	s_add_u32 s4, s45, s2
	v_div_scale_f32 v34, s[2:3], v33, v33, 1.0
	v_rcp_f32_e32 v35, v34
	v_div_scale_f32 v36, vcc, 1.0, v33, 1.0
	v_cmp_lt_f32_e64 s[2:3], 0, v33
	v_fma_f32 v37, -v34, v35, 1.0
	v_fmac_f32_e32 v35, v37, v35
	v_mul_f32_e32 v37, v36, v35
	v_fma_f32 v38, -v34, v37, v36
	v_fmac_f32_e32 v37, v38, v35
	v_fma_f32 v34, -v34, v37, v36
	v_div_fmas_f32 v34, v34, v35, v37
	v_div_fixup_f32 v33, v34, v33, 1.0
	v_cndmask_b32_e64 v33, 0, v33, s[2:3]
	v_mov_b32_e32 v80, v246
	s_addc_u32 s5, s44, 0
	s_mov_b32 s19, s81
	s_mov_b32 s21, s81
	v_mov_b32_e32 v34, v215
	v_mov_b32_e32 v35, v215
	v_mov_b32_e32 v36, v215
	v_mov_b32_e32 v37, v215
	v_mov_b32_e32 v38, v215
	v_mov_b32_e32 v39, v215
	v_mov_b32_e32 v40, v215
	v_mov_b32_e32 v41, v215
	v_mov_b32_e32 v42, v215
	v_mov_b32_e32 v43, v215
	v_mov_b32_e32 v44, v215
	v_mov_b32_e32 v45, v215
	v_mov_b32_e32 v46, v215
	v_mov_b32_e32 v47, v215
	s_waitcnt vmcnt(0)
	v_mul_f32_e32 v32, v32, v33
	v_mul_f32_e32 v0, v0, v32
	v_mul_f32_e32 v1, v1, v32
	v_mul_f32_e32 v16, v16, v32
	v_mul_f32_e32 v17, v17, v32
	v_mul_f32_e32 v2, v2, v32
	v_mul_f32_e32 v18, v18, v32
	v_mul_f32_e32 v3, v3, v32
	v_mul_f32_e32 v19, v19, v32
	v_mul_f32_e32 v4, v4, v32
	v_mul_f32_e32 v20, v20, v32
	v_mul_f32_e32 v5, v5, v32
	v_mul_f32_e32 v21, v21, v32
	v_mul_f32_e32 v6, v6, v32
	v_mul_f32_e32 v22, v22, v32
	v_mul_f32_e32 v7, v7, v32
	v_mul_f32_e32 v23, v23, v32
	v_mul_f32_e32 v8, v8, v32
	v_mul_f32_e32 v24, v24, v32
	v_mul_f32_e32 v9, v9, v32
	v_mul_f32_e32 v25, v25, v32
	v_mul_f32_e32 v10, v10, v32
	v_mul_f32_e32 v26, v26, v32
	v_mul_f32_e32 v11, v11, v32
	v_mul_f32_e32 v27, v27, v32
	v_mul_f32_e32 v12, v12, v32
	v_mul_f32_e32 v28, v28, v32
	v_mul_f32_e32 v13, v13, v32
	v_mul_f32_e32 v29, v29, v32
	v_mul_f32_e32 v14, v14, v32
	v_mul_f32_e32 v30, v30, v32
	v_mul_f32_e32 v15, v15, v32
	v_mul_f32_e32 v31, v31, v32
	ds_write2st64_b32 v164, v0, v1 offset1:8
	ds_write2st64_b32 v164, v16, v17 offset0:128 offset1:136
	ds_write2st64_b32 v164, v2, v3 offset0:16 offset1:24
	ds_write2st64_b32 v164, v18, v19 offset0:144 offset1:152
	ds_write2st64_b32 v164, v4, v5 offset0:32 offset1:40
	ds_write2st64_b32 v164, v20, v21 offset0:160 offset1:168
	ds_write2st64_b32 v164, v6, v7 offset0:48 offset1:56
	ds_write2st64_b32 v164, v22, v23 offset0:176 offset1:184
	ds_write2st64_b32 v164, v8, v9 offset0:64 offset1:72
	ds_write2st64_b32 v164, v24, v25 offset0:192 offset1:200
	ds_write2st64_b32 v164, v10, v11 offset0:80 offset1:88
	ds_write2st64_b32 v164, v26, v27 offset0:208 offset1:216
	ds_write2st64_b32 v164, v12, v13 offset0:96 offset1:104
	ds_write2st64_b32 v164, v28, v29 offset0:224 offset1:232
	ds_write2st64_b32 v164, v14, v15 offset0:112 offset1:120
	ds_write2st64_b32 v164, v30, v31 offset0:240 offset1:248
	v_mov_b64_e32 v[2:3], s[16:17]
	v_and_b32_e32 v0, 31, v80
	v_bfe_u32 v1, v80, 5, 1
	v_or_b32_e32 v4, s39, v0
	v_mad_u64_u32 v[2:3], s[2:3], v4, s65, v[2:3]
	v_lshlrev_b32_e32 v4, 4, v1
	v_mov_b32_e32 v5, v215
	v_lshl_add_u64 v[2:3], v[2:3], 0, v[4:5]
	global_load_dwordx4 v[112:115], v[2:3], off offset:2368
	global_load_dwordx4 v[116:119], v[2:3], off offset:2400
	global_load_dwordx4 v[120:123], v[2:3], off offset:2432
	global_load_dwordx4 v[124:127], v[2:3], off offset:2464
	v_and_b32_e32 v6, 63, v80
	s_add_i32 s2, s40, 0xfffffe01
	v_mul_u32_u24_e32 v2, 0xa00, v6
	s_lshr_b32 s2, s2, 6
	v_lshlrev_b32_e32 v2, 1, v2
	v_mov_b32_e32 v3, v215
	s_cmpk_gt_u32 s40, 0x1ff
	v_lshl_add_u64 v[2:3], s[4:5], 0, v[2:3]
	s_cselect_b32 s16, s2, 0
	v_lshl_add_u64 v[2:3], v[2:3], 0, s[18:19]
	s_mov_b64 s[2:3], 0x1140
	v_lshl_add_u64 v[160:161], v[2:3], 0, s[2:3]
	v_bfe_u32 v2, v80, 2, 4
	v_or_b32_e32 v2, s59, v2
	v_mul_u32_u24_e32 v2, 0xa00, v2
	v_lshlrev_b32_e32 v2, 1, v2
	v_mov_b32_e32 v3, v215
	v_lshl_add_u64 v[2:3], s[4:5], 0, v[2:3]
	v_lshl_add_u64 v[4:5], v[2:3], 0, s[20:21]
	v_lshlrev_b32_e32 v2, 3, v80
	v_and_b32_e32 v2, 24, v2
	v_lshlrev_b32_e32 v6, 1, v2
	v_mov_b32_e32 v7, v215
	v_lshl_add_u64 v[4:5], v[4:5], 0, v[6:7]
	s_mov_b64 s[2:3], 0x1240
	v_lshl_add_u64 v[162:163], v[4:5], 0, s[2:3]
	s_min_u32 s2, s16, s43
	s_mul_i32 s3, s2, 0x56
	s_lshr_b32 s3, s3, 8
	s_mul_i32 s3, s3, 3
	s_sub_i32 s3, s2, s3
	s_and_b32 s3, s3, 0xff
	s_lshl_b32 s3, s3, 14
	s_add_i32 s3, s3, 0
	s_mul_i32 s80, s2, 0x50000
	v_mov_b32_e32 v32, v215
	v_mov_b32_e32 v33, v215
	v_lshl_add_u64 v[4:5], v[160:161], 0, s[80:81]
	s_add_i32 m0, s3, s89
	s_add_i32 s2, s3, s95
	global_load_lds_dwordx4 v[4:5], off
	s_add_i32 m0, s2, 0x2000
	s_or_b32 s2, s16, 1
	s_min_u32 s2, s2, s43
	s_mul_i32 s3, s2, 0x56
	s_lshr_b32 s3, s3, 8
	s_mul_i32 s3, s3, 3
	s_sub_i32 s3, s2, s3
	v_lshl_add_u64 v[4:5], v[162:163], 0, s[80:81]
	s_and_b32 s3, s3, 0xff
	s_mul_i32 s80, s2, 0x50000
	s_or_b32 s2, s16, 2
	s_lshl_b32 s3, s3, 14
	s_min_u32 s2, s2, s43
	s_add_i32 s4, s3, 0
	s_mul_i32 s3, s2, 0x56
	s_lshr_b32 s3, s3, 8
	s_mul_i32 s3, s3, 3
	s_sub_i32 s3, s2, s3
	s_and_b32 s3, s3, 0xff
	global_load_lds_dwordx4 v[4:5], off
	v_lshl_add_u64 v[4:5], v[160:161], 0, s[80:81]
	s_add_i32 m0, s4, s89
	s_lshl_b32 s5, s3, 14
	s_mul_i32 s2, s2, 0x50000
	s_mov_b32 s3, s81
	global_load_lds_dwordx4 v[4:5], off
	v_lshl_add_u64 v[4:5], v[160:161], 0, s[2:3]
	s_add_i32 m0, s61, s5
	s_add_i32 s2, s4, s95
	global_load_lds_dwordx4 v[4:5], off
	s_add_i32 m0, s2, 0x2000
	s_mul_hi_u32 s2, s16, 0x55555556
	s_mul_i32 s2, s2, 3
	s_sub_i32 s2, s16, s2
	v_lshl_add_u64 v[4:5], v[162:163], 0, s[80:81]
	s_lshl_b32 s2, s2, 14
	global_load_lds_dwordx4 v[4:5], off
	s_add_i32 s2, s2, 0
	v_lshlrev_b32_e32 v166, 10, v1
	v_lshlrev_b32_e32 v167, 4, v0
	s_waitcnt vmcnt(2) lgkmcnt(0)
	s_barrier
; #define AT_KFRAG(t) do { \
;         LAS unsigned char* Kb_ = lds + ((t) % 3) * SLOT + hi * 1024 + r32 * 16; \
;         _Pragma("unroll") for (int ds = 0; ds < NDS; ++ds) { kf[2 * ds] = *(LAS bf16x8*)(Kb_ + ds * 2048); kf[2 * ds + 1] = *(LAS bf16x8*)(Kb_ + ds * 2048 + 512); } } while (0)
; template <int DQK, int MODE> ...
;     ...
;     { AT_KFRAG(kt_lo); asm volatile("s_waitcnt lgkmcnt(0)\n\ts_barrier" ::: "memory");
;       const float b_ = AT_BIAS(kt_lo); AT_QKM(pa0, pa1, AT_SPLAT(b_)); }
;     ...
;     for (int kt = kt_lo; kt <= kt_hi; kt += 2) {
	v_add3_u32 v3, s2, v166, v167
	ds_read_b128 v[4:7], v3
	s_waitcnt vmcnt(2) lgkmcnt(0)
	v_mfma_f32_32x32x16_bf16 v[48:63], v[4:7], v[112:115], 0
	ds_read_b128 v[4:7], v3 offset:512
	s_cmp_gt_u32 s16, s43
	s_waitcnt lgkmcnt(0)
	v_mfma_f32_32x32x16_bf16 v[64:79], v[4:7], v[112:115], 0
	ds_read_b128 v[4:7], v3 offset:2048
	s_waitcnt lgkmcnt(0)
	v_mfma_f32_32x32x16_bf16 v[48:63], v[4:7], v[116:119], v[48:63]
	ds_read_b128 v[4:7], v3 offset:2560
	s_waitcnt lgkmcnt(0)
	v_mfma_f32_32x32x16_bf16 v[64:79], v[4:7], v[116:119], v[64:79]
	ds_read_b128 v[4:7], v3 offset:4096
	s_waitcnt lgkmcnt(0)
	v_mfma_f32_32x32x16_bf16 v[48:63], v[4:7], v[120:123], v[48:63]
	ds_read_b128 v[4:7], v3 offset:4608
	s_waitcnt lgkmcnt(0)
	v_mfma_f32_32x32x16_bf16 v[64:79], v[4:7], v[120:123], v[64:79]
	ds_read_b128 v[4:7], v3 offset:6144
	s_waitcnt lgkmcnt(0)
	v_mfma_f32_32x32x16_bf16 v[48:63], v[4:7], v[124:127], v[48:63]
	ds_read_b128 v[4:7], v3 offset:6656
	s_waitcnt lgkmcnt(0)
	s_barrier
	s_waitcnt lgkmcnt(0)
	v_mfma_f32_32x32x16_bf16 v[64:79], v[4:7], v[124:127], v[64:79]
	s_cbranch_scc1 .LBB0_711
	v_lshlrev_b32_e32 v5, 4, v80
	v_lshlrev_b32_e32 v4, 2, v1
	s_lshl_b32 s2, s16, 14
	v_lshlrev_b32_e32 v1, 8, v1
	v_and_b32_e32 v5, 0xc0, v5
	v_lshlrev_b32_e32 v3, 1, v80
	v_or3_b32 v1, s2, v1, v5
	s_add_i32 s2, s56, s40
	v_and_b32_e32 v3, 32, v3
	v_add_u32_e32 v0, s2, v0
	v_or3_b32 v1, v1, v3, v2
	v_sub_u32_e32 v0, v0, v4
	s_lshl_b32 s20, s16, 6
	v_mov_b32_e32 v171, 0
	v_add3_u32 v168, 0, v166, v167
	s_add_i32 s17, s39, 0xfffffe20
	s_add_i32 s18, s16, 4
	v_add_u32_e32 v169, 0, v1
	s_add_i32 s19, s16, 1
	v_subrev_u32_e32 v170, s20, v0
	s_mov_b64 s[2:3], 0
	v_mov_b32_e32 v165, 0
	v_mov_b32_e32 v16, 0
	v_mov_b32_e32 v17, v171
	v_mov_b32_e32 v18, v171
	v_mov_b32_e32 v19, v171
	v_mov_b32_e32 v20, v171
	v_mov_b32_e32 v21, v171
	v_mov_b32_e32 v22, v171
	v_mov_b32_e32 v23, v171
	v_mov_b32_e32 v24, v171
	v_mov_b32_e32 v25, v171
	v_mov_b32_e32 v26, v171
	v_mov_b32_e32 v27, v171
	v_mov_b32_e32 v28, v171
	v_mov_b32_e32 v29, v171
	v_mov_b32_e32 v30, v171
	v_mov_b32_e32 v31, v171
	v_mov_b32_e32 v0, v171
	v_mov_b32_e32 v1, v171
	v_mov_b32_e32 v2, v171
	v_mov_b32_e32 v3, v171
	v_mov_b32_e32 v4, v171
	v_mov_b32_e32 v5, v171
	v_mov_b32_e32 v6, v171
	v_mov_b32_e32 v7, v171
	v_mov_b32_e32 v8, v171
	v_mov_b32_e32 v9, v171
	v_mov_b32_e32 v10, v171
	v_mov_b32_e32 v11, v171
	v_mov_b32_e32 v12, v171
	v_mov_b32_e32 v13, v171
	v_mov_b32_e32 v14, v171
	v_mov_b32_e32 v15, v171
	v_readfirstlane_b32 s86, v160
	v_readfirstlane_b32 s87, v161
	v_readfirstlane_b32 s98, v162
	v_readfirstlane_b32 s99, v163
	s_nop 1
	v_subrev_u32_e32 v200, s86, v160
	v_subrev_u32_e32 v202, s98, v162
	s_branch .LBB0_702

.LBB0_702:
	s_add_i32 s4, s18, -1
	s_min_i32 s4, s4, s43
	s_mul_hi_u32 s5, s4, 0xaaaaaaab
	s_lshr_b32 s5, s5, 1
	s_mul_i32 s5, s5, 3
	s_sub_i32 s5, s4, s5
	s_add_i32 s21, s18, -2
	s_lshl_b32 s5, s5, 14
	s_mul_i32 s80, s4, 0x50000
	s_min_i32 s4, s21, s43
	s_add_i32 s23, s5, 0
	s_mul_hi_u32 s5, s4, 0xaaaaaaab
	s_lshr_b32 s5, s5, 1
	s_mul_i32 s5, s5, 3
	s_sub_i32 s5, s4, s5
	s_lshl_b32 s5, s5, 14
	v_add_u32_e32 v80, s80, v200
	s_add_i32 m0, s23, s89
	s_add_i32 s22, s5, 0
	s_mul_i32 s4, s4, 0x50000
	s_mov_b32 s5, s81
	global_load_lds_dwordx4 v80, s[86:87]
	v_add_u32_e32 v80, s4, v202
	s_add_i32 s4, s22, s95
	s_add_i32 m0, s4, 0x2000
	s_add_i32 s4, s20, 63
	global_load_lds_dwordx4 v80, s[98:99]
	s_sub_i32 s5, s20, 31
	s_cmp_gt_i32 s5, s39
	s_cbranch_scc1 .Ltsk702_d1
	s_add_i32 s5, s20, 0x23e
	s_cmp_lt_i32 s5, s39
	s_cbranch_scc1 .Ltsk702_f1
	s_cmp_gt_u32 s4, s39
	s_cselect_b64 s[4:5], -1, 0
	s_cmp_lt_i32 s20, s17
	s_cselect_b64 s[6:7], -1, 0
	s_or_b64 s[4:5], s[4:5], s[6:7]
	s_andn2_b64 vcc, exec, s[4:5]
	s_cbranch_vccnz .LBB0_704
	v_add_u32_e32 v80, 0x7b, v170
	v_add_u32_e32 v81, 0x5b, v170
	v_cmp_gt_u32_e32 vcc, s94, v80
	v_add_u32_e32 v80, 0x7a, v170
	s_nop 0
	v_cndmask_b32_e32 v48, v249, v48, vcc
	v_cmp_gt_u32_e32 vcc, s94, v81
	v_add_u32_e32 v81, 0x5a, v170
	s_nop 0
	v_cndmask_b32_e32 v64, v249, v64, vcc
	v_cmp_gt_u32_e32 vcc, s94, v80
	v_add_u32_e32 v80, 0x79, v170
	s_nop 0
	v_cndmask_b32_e32 v49, v249, v49, vcc
	v_cmp_gt_u32_e32 vcc, s94, v81
	v_add_u32_e32 v81, 0x59, v170
	s_nop 0
	v_cndmask_b32_e32 v65, v249, v65, vcc
	v_cmp_gt_u32_e32 vcc, s94, v80
	v_add_u32_e32 v80, 0x78, v170
	s_nop 0
	v_cndmask_b32_e32 v50, v249, v50, vcc
	v_cmp_gt_u32_e32 vcc, s94, v81
	v_add_u32_e32 v81, 0x58, v170
	s_nop 0
	v_cndmask_b32_e32 v66, v249, v66, vcc
	v_cmp_gt_u32_e32 vcc, s94, v80
	v_add_u32_e32 v80, 0x73, v170
	s_nop 0
	v_cndmask_b32_e32 v51, v249, v51, vcc
	v_cmp_gt_u32_e32 vcc, s94, v81
	v_add_u32_e32 v81, 0x53, v170
	s_nop 0
	v_cndmask_b32_e32 v67, v249, v67, vcc
	v_cmp_gt_u32_e32 vcc, s94, v80
	v_add_u32_e32 v80, 0x72, v170
	s_nop 0
	v_cndmask_b32_e32 v52, v249, v52, vcc
	v_cmp_gt_u32_e32 vcc, s94, v81
	v_add_u32_e32 v81, 0x52, v170
	s_nop 0
	v_cndmask_b32_e32 v68, v249, v68, vcc
	v_cmp_gt_u32_e32 vcc, s94, v80
	v_add_u32_e32 v80, 0x71, v170
	s_nop 0
	v_cndmask_b32_e32 v53, v249, v53, vcc
	v_cmp_gt_u32_e32 vcc, s94, v81
	v_add_u32_e32 v81, 0x51, v170
	s_nop 0
	v_cndmask_b32_e32 v69, v249, v69, vcc
	v_cmp_gt_u32_e32 vcc, s94, v80
	v_add_u32_e32 v80, 0x70, v170
	s_nop 0
	v_cndmask_b32_e32 v54, v249, v54, vcc
	v_cmp_gt_u32_e32 vcc, s94, v81
	v_add_u32_e32 v81, 0x50, v170
	s_nop 0
	v_cndmask_b32_e32 v70, v249, v70, vcc
	v_cmp_gt_u32_e32 vcc, s94, v80
	v_add_u32_e32 v80, 0x6b, v170
	s_nop 0
	v_cndmask_b32_e32 v55, v249, v55, vcc
	v_cmp_gt_u32_e32 vcc, s94, v81
	v_add_u32_e32 v81, 0x4b, v170
	s_nop 0
	v_cndmask_b32_e32 v71, v249, v71, vcc
	v_cmp_gt_u32_e32 vcc, s94, v80
	v_add_u32_e32 v80, 0x6a, v170
	s_nop 0
	v_cndmask_b32_e32 v56, v249, v56, vcc
	v_cmp_gt_u32_e32 vcc, s94, v81
	v_add_u32_e32 v81, 0x4a, v170
	s_nop 0
	v_cndmask_b32_e32 v72, v249, v72, vcc
	v_cmp_gt_u32_e32 vcc, s94, v80
	v_add_u32_e32 v80, 0x69, v170
	s_nop 0
	v_cndmask_b32_e32 v57, v249, v57, vcc
	v_cmp_gt_u32_e32 vcc, s94, v81
	v_add_u32_e32 v81, 0x49, v170
	s_nop 0
	v_cndmask_b32_e32 v73, v249, v73, vcc
	v_cmp_gt_u32_e32 vcc, s94, v80
	v_add_u32_e32 v80, 0x68, v170
	s_nop 0
	v_cndmask_b32_e32 v58, v249, v58, vcc
	v_cmp_gt_u32_e32 vcc, s94, v81
	v_add_u32_e32 v81, 0x48, v170
	s_nop 0
	v_cndmask_b32_e32 v74, v249, v74, vcc
	v_cmp_gt_u32_e32 vcc, s94, v80
	v_add_u32_e32 v80, 0x63, v170
	s_nop 0
	v_cndmask_b32_e32 v59, v249, v59, vcc
	v_cmp_gt_u32_e32 vcc, s94, v81
	v_add_u32_e32 v81, 0x43, v170
	s_nop 0
	v_cndmask_b32_e32 v75, v249, v75, vcc
	v_cmp_gt_u32_e32 vcc, s94, v80
	v_add_u32_e32 v80, 0x62, v170
	s_nop 0
	v_cndmask_b32_e32 v60, v249, v60, vcc
	v_cmp_gt_u32_e32 vcc, s94, v81
	v_add_u32_e32 v81, 0x42, v170
	s_nop 0
	v_cndmask_b32_e32 v76, v249, v76, vcc
	v_cmp_gt_u32_e32 vcc, s94, v80
	v_add_u32_e32 v80, 0x61, v170
	s_nop 0
	v_cndmask_b32_e32 v61, v249, v61, vcc
	v_cmp_gt_u32_e32 vcc, s94, v81
	v_add_u32_e32 v81, 0x41, v170
	s_nop 0
	v_cndmask_b32_e32 v77, v249, v77, vcc
	v_cmp_gt_u32_e32 vcc, s94, v80
	v_add_u32_e32 v80, 0x60, v170
	s_nop 0
	v_cndmask_b32_e32 v62, v249, v62, vcc
	v_cmp_gt_u32_e32 vcc, s94, v81
	v_add_u32_e32 v81, 64, v170
	s_nop 0
	v_cndmask_b32_e32 v78, v249, v78, vcc
	v_cmp_gt_u32_e32 vcc, s94, v80
	s_nop 1
	v_cndmask_b32_e32 v63, v249, v63, vcc
	v_cmp_gt_u32_e32 vcc, s94, v81
	s_nop 1
	v_cndmask_b32_e32 v79, v249, v79, vcc

.Ltsk702_s2:
	s_min_i32 s4, s18, s43
	s_mul_hi_u32 s5, s4, 0xaaaaaaab
	s_lshr_b32 s5, s5, 1
	s_mul_i32 s5, s5, 3
	s_sub_i32 s5, s4, s5
	s_lshl_b32 s6, s5, 14
	s_mul_i32 s4, s4, 0x50000
	s_mov_b32 s5, s81
	v_add_u32_e32 v48, s4, v200
	s_add_i32 m0, s61, s6
	s_add_i32 s4, s23, s95
	global_load_lds_dwordx4 v48, s[86:87]
	v_add_u32_e32 v48, s80, v202
	s_add_i32 m0, s4, 0x2000
	s_add_i32 s6, s20, 64
	global_load_lds_dwordx4 v48, s[98:99]
	s_sub_i32 s5, s6, 31
	s_cmp_gt_i32 s5, s39
	s_cbranch_scc1 .Ltsk702_d2
	s_add_i32 s5, s6, 0x23e
	s_cmp_lt_i32 s5, s39
	s_cbranch_scc1 .Ltsk702_f2
	s_add_i32 s4, s20, 0x7f
	s_cmp_gt_u32 s4, s39
	s_cselect_b64 s[4:5], -1, 0
	s_cmp_lt_i32 s6, s17
	s_cselect_b64 s[6:7], -1, 0
	s_or_b64 s[4:5], s[4:5], s[6:7]
	s_andn2_b64 vcc, exec, s[4:5]
	s_cbranch_vccnz .LBB0_709
	v_add_u32_e32 v48, 59, v170
	v_add_u32_e32 v49, 27, v170
	v_cmp_gt_u32_e32 vcc, s94, v48
	v_add_u32_e32 v48, 58, v170
	s_nop 0
	v_cndmask_b32_e32 v96, v249, v96, vcc
	v_cmp_gt_u32_e32 vcc, s94, v49
	v_add_u32_e32 v49, 26, v170
	s_nop 0
	v_cndmask_b32_e32 v80, v249, v80, vcc
	v_cmp_gt_u32_e32 vcc, s94, v48
	v_add_u32_e32 v48, 57, v170
	s_nop 0
	v_cndmask_b32_e32 v97, v249, v97, vcc
	v_cmp_gt_u32_e32 vcc, s94, v49
	v_add_u32_e32 v49, 25, v170
	s_nop 0
	v_cndmask_b32_e32 v81, v249, v81, vcc
	v_cmp_gt_u32_e32 vcc, s94, v48
	v_add_u32_e32 v48, 56, v170
	s_nop 0
	v_cndmask_b32_e32 v98, v249, v98, vcc
	v_cmp_gt_u32_e32 vcc, s94, v49
	v_add_u32_e32 v49, 24, v170
	s_nop 0
	v_cndmask_b32_e32 v82, v249, v82, vcc
	v_cmp_gt_u32_e32 vcc, s94, v48
	v_add_u32_e32 v48, 51, v170
	s_nop 0
	v_cndmask_b32_e32 v99, v249, v99, vcc
	v_cmp_gt_u32_e32 vcc, s94, v49
	v_add_u32_e32 v49, 19, v170
	s_nop 0
	v_cndmask_b32_e32 v83, v249, v83, vcc
	v_cmp_gt_u32_e32 vcc, s94, v48
	v_add_u32_e32 v48, 50, v170
	s_nop 0
	v_cndmask_b32_e32 v100, v249, v100, vcc
	v_cmp_gt_u32_e32 vcc, s94, v49
	v_add_u32_e32 v49, 18, v170
	s_nop 0
	v_cndmask_b32_e32 v84, v249, v84, vcc
	v_cmp_gt_u32_e32 vcc, s94, v48
	v_add_u32_e32 v48, 49, v170
	s_nop 0
	v_cndmask_b32_e32 v101, v249, v101, vcc
	v_cmp_gt_u32_e32 vcc, s94, v49
	v_add_u32_e32 v49, 17, v170
	s_nop 0
	v_cndmask_b32_e32 v85, v249, v85, vcc
	v_cmp_gt_u32_e32 vcc, s94, v48
	v_add_u32_e32 v48, 48, v170
	s_nop 0
	v_cndmask_b32_e32 v102, v249, v102, vcc
	v_cmp_gt_u32_e32 vcc, s94, v49
	v_add_u32_e32 v49, 16, v170
	s_nop 0
	v_cndmask_b32_e32 v86, v249, v86, vcc
	v_cmp_gt_u32_e32 vcc, s94, v48
	v_add_u32_e32 v48, 43, v170
	s_nop 0
	v_cndmask_b32_e32 v103, v249, v103, vcc
	v_cmp_gt_u32_e32 vcc, s94, v49
	v_add_u32_e32 v49, 11, v170
	s_nop 0
	v_cndmask_b32_e32 v87, v249, v87, vcc
	v_cmp_gt_u32_e32 vcc, s94, v48
	v_add_u32_e32 v48, 42, v170
	s_nop 0
	v_cndmask_b32_e32 v104, v249, v104, vcc
	v_cmp_gt_u32_e32 vcc, s94, v49
	v_add_u32_e32 v49, 10, v170
	s_nop 0
	v_cndmask_b32_e32 v88, v249, v88, vcc
	v_cmp_gt_u32_e32 vcc, s94, v48
	v_add_u32_e32 v48, 41, v170
	s_nop 0
	v_cndmask_b32_e32 v105, v249, v105, vcc
	v_cmp_gt_u32_e32 vcc, s94, v49
	v_add_u32_e32 v49, 9, v170
	s_nop 0
	v_cndmask_b32_e32 v89, v249, v89, vcc
	v_cmp_gt_u32_e32 vcc, s94, v48
	v_add_u32_e32 v48, 40, v170
	s_nop 0
	v_cndmask_b32_e32 v106, v249, v106, vcc
	v_cmp_gt_u32_e32 vcc, s94, v49
	v_add_u32_e32 v49, 8, v170
	s_nop 0
	v_cndmask_b32_e32 v90, v249, v90, vcc
	v_cmp_gt_u32_e32 vcc, s94, v48
	v_add_u32_e32 v48, 35, v170
	s_nop 0
	v_cndmask_b32_e32 v107, v249, v107, vcc
	v_cmp_gt_u32_e32 vcc, s94, v49
	v_add_u32_e32 v49, 3, v170
	s_nop 0
	v_cndmask_b32_e32 v91, v249, v91, vcc
	v_cmp_gt_u32_e32 vcc, s94, v48
	v_add_u32_e32 v48, 34, v170
	s_nop 0
	v_cndmask_b32_e32 v108, v249, v108, vcc
	v_cmp_gt_u32_e32 vcc, s94, v49
	v_add_u32_e32 v49, 2, v170
	s_nop 0
	v_cndmask_b32_e32 v92, v249, v92, vcc
	v_cmp_gt_u32_e32 vcc, s94, v48
	v_add_u32_e32 v48, 33, v170
	s_nop 0
	v_cndmask_b32_e32 v109, v249, v109, vcc
	v_cmp_gt_u32_e32 vcc, s94, v49
	v_add_u32_e32 v49, 1, v170
	s_nop 0
	v_cndmask_b32_e32 v93, v249, v93, vcc
	v_cmp_gt_u32_e32 vcc, s94, v48
	v_add_u32_e32 v48, 32, v170
	s_nop 0
	v_cndmask_b32_e32 v110, v249, v110, vcc
	v_cmp_gt_u32_e32 vcc, s94, v49
	s_nop 1
	v_cndmask_b32_e32 v94, v249, v94, vcc
	v_cmp_gt_u32_e32 vcc, s94, v48
	s_nop 1
	v_cndmask_b32_e32 v111, v249, v111, vcc
	v_cmp_gt_u32_e32 vcc, s94, v170
	s_nop 1
	v_cndmask_b32_e32 v95, v249, v95, vcc

; __device__ __forceinline__ float oload(LAS unsigned char* lds, int tid, int i) { return ((LAS float*)(lds + OSAVE_OFF) + tid)[i * 512]; }
; __device__ __forceinline__ void attn_phase(LAS unsigned char* lds, int* counter, const bf16_t* __restrict__ P, const bf16_t* __restrict__ Qm, const bf16_t* __restrict__ Kmla, ...
;     ...
;             const float g0 = gates[row * 24 + head * 3 + 0], sc2 = linv * gates[row * 24 + head * 3 + 2];
;             const bf16_t* oc = ocmp + row * 512 + head * 64;
; #pragma unroll
;             for (int dh = 0; dh < 2; ++dh)
; #pragma unroll
;                 for (int a = 0; a < 4; ++a) {
;                     const u32x2 raw = *(const u32x2*)(oc + 32 * dh + 8 * a + 4 * hi);
;                     const float c0 = __uint_as_float(raw.x << 16), c1 = __uint_as_float(raw.x & 0xffff0000u), c2 = __uint_as_float(raw.y << 16), c3 = __uint_as_float(raw.y & 0xffff0000u);
;                     o[dh][4 * a + 0] = o[dh][4 * a + 0] * sc2 + oload(lds, tid, 16 * dh + 4 * a + 0) + g0 * c0;
;                     o[dh][4 * a + 1] = o[dh][4 * a + 1] * sc2 + oload(lds, tid, 16 * dh + 4 * a + 1) + g0 * c1;
;                     o[dh][4 * a + 2] = o[dh][4 * a + 2] * sc2 + oload(lds, tid, 16 * dh + 4 * a + 2) + g0 * c2;
;                     o[dh][4 * a + 3] = o[dh][4 * a + 3] * sc2 + oload(lds, tid, 16 * dh + 4 * a + 3) + g0 * c3;
;                 }
;             store_o_bf16(Omix + row * DM + 512 + head * 64, o, hi);
.LBB0_712:
	v_readlane_b32 s86, v254, 37
	v_readlane_b32 s87, v254, 38
	s_waitcnt vmcnt(0) lgkmcnt(0)
	s_barrier
	s_nop 3
	global_load_dword v70, v[158:159], off offset:8
	v_lshlrev_b64 v[32:33], 10, v[156:157]
	s_lshl_b32 s80, s42, 1
	v_lshl_add_u64 v[32:33], s[8:9], 0, v[32:33]
	v_lshlrev_b32_e32 v34, 3, v190
	v_mov_b32_e32 v35, v215
	v_lshl_add_u64 v[32:33], v[32:33], 0, s[80:81]
	v_lshl_add_u64 v[34:35], v[32:33], 0, v[34:35]
	global_load_dwordx2 v[36:37], v[34:35], off
	global_load_dwordx2 v[38:39], v[34:35], off offset:16
	global_load_dwordx2 v[40:41], v[34:35], off offset:32
	global_load_dwordx2 v[42:43], v[34:35], off offset:48
	global_load_dwordx2 v[44:45], v[34:35], off offset:64
	global_load_dword v32, v[158:159], off
	global_load_dwordx2 v[46:47], v[34:35], off offset:80
	global_load_dwordx2 v[48:49], v[34:35], off offset:96
	ds_read2st64_b32 v[50:51], v164 offset1:8
	ds_read2st64_b32 v[52:53], v164 offset0:16 offset1:24
	ds_read2st64_b32 v[54:55], v164 offset0:32 offset1:40
	ds_read2st64_b32 v[56:57], v164 offset0:48 offset1:56
	global_load_dwordx2 v[34:35], v[34:35], off offset:112
	v_mov_b32_e32 v33, v165
	s_nop 1
	v_permlane32_swap_b32_e32 v165, v33
	v_add_f32_e32 v33, v165, v33
	v_div_scale_f32 v71, s[2:3], v33, v33, 1.0
	v_rcp_f32_e32 v72, v71
	v_div_scale_f32 v73, vcc, 1.0, v33, 1.0
	ds_read2st64_b32 v[58:59], v164 offset0:64 offset1:72
	ds_read2st64_b32 v[60:61], v164 offset0:80 offset1:88
	ds_read2st64_b32 v[62:63], v164 offset0:96 offset1:104
	ds_read2st64_b32 v[64:65], v164 offset0:112 offset1:120
	ds_read2st64_b32 v[66:67], v164 offset0:128 offset1:136
	v_fma_f32 v74, -v71, v72, 1.0
	v_fmac_f32_e32 v72, v74, v72
	v_mul_f32_e32 v74, v73, v72
	v_fma_f32 v75, -v71, v74, v73
	v_fmac_f32_e32 v74, v75, v72
	v_fma_f32 v71, -v71, v74, v73
	ds_read2st64_b32 v[68:69], v164 offset0:144 offset1:152
	v_div_fmas_f32 v71, v71, v72, v74
	v_div_fixup_f32 v71, v71, v33, 1.0
	v_cmp_lt_f32_e32 vcc, 0, v33
	v_readlane_b32 s2, v254, 46
	v_readlane_b32 s3, v254, 47
	v_cndmask_b32_e32 v33, 0, v71, vcc
	v_cmp_eq_u32_e32 vcc, 0, v190
	s_waitcnt vmcnt(0)
	v_mul_f32_e32 v70, v70, v33
	s_waitcnt lgkmcnt(9)
	v_pk_fma_f32 v[16:17], v[16:17], v[70:71], v[50:51] op_sel_hi:[1,0,1]
	s_waitcnt lgkmcnt(8)
	v_pk_fma_f32 v[18:19], v[18:19], v[70:71], v[52:53] op_sel_hi:[1,0,1]
	s_waitcnt lgkmcnt(1)
	v_pk_fma_f32 v[50:51], v[0:1], v[70:71], v[66:67] op_sel_hi:[1,0,1]
	v_lshlrev_b32_e32 v0, 16, v36
	v_and_b32_e32 v1, 0xffff0000, v36
	v_lshlrev_b32_e32 v36, 16, v37
	v_and_b32_e32 v37, 0xffff0000, v37
	v_pk_fma_f32 v[0:1], v[32:33], v[0:1], v[16:17] op_sel_hi:[0,1,1]
	v_pk_fma_f32 v[16:17], v[32:33], v[36:37], v[18:19] op_sel_hi:[0,1,1]
	s_waitcnt lgkmcnt(0)
	v_pk_fma_f32 v[36:37], v[2:3], v[70:71], v[68:69] op_sel_hi:[1,0,1]
	ds_read2st64_b32 v[2:3], v164 offset0:176 offset1:184
	v_pk_fma_f32 v[20:21], v[20:21], v[70:71], v[54:55] op_sel_hi:[1,0,1]
	v_pk_fma_f32 v[22:23], v[22:23], v[70:71], v[56:57] op_sel_hi:[1,0,1]
	v_pk_fma_f32 v[24:25], v[24:25], v[70:71], v[58:59] op_sel_hi:[1,0,1]
	v_pk_fma_f32 v[26:27], v[26:27], v[70:71], v[60:61] op_sel_hi:[1,0,1]
	s_waitcnt lgkmcnt(0)
	v_pk_fma_f32 v[6:7], v[6:7], v[70:71], v[2:3] op_sel_hi:[1,0,1]
	ds_read2st64_b32 v[2:3], v164 offset0:208 offset1:216
	v_pk_fma_f32 v[28:29], v[28:29], v[70:71], v[62:63] op_sel_hi:[1,0,1]
	v_pk_fma_f32 v[30:31], v[30:31], v[70:71], v[64:65] op_sel_hi:[1,0,1]
	v_lshlrev_b32_e32 v52, 16, v38
	v_and_b32_e32 v53, 0xffff0000, v38
	v_lshlrev_b32_e32 v38, 16, v39
	v_and_b32_e32 v39, 0xffff0000, v39
	v_lshlrev_b32_e32 v54, 16, v40
	v_and_b32_e32 v55, 0xffff0000, v40
	v_lshlrev_b32_e32 v40, 16, v41
	v_and_b32_e32 v41, 0xffff0000, v41
	v_lshlrev_b32_e32 v56, 16, v42
	v_and_b32_e32 v57, 0xffff0000, v42
	v_lshlrev_b32_e32 v42, 16, v43
	v_and_b32_e32 v43, 0xffff0000, v43
	v_pk_fma_f32 v[18:19], v[32:33], v[52:53], v[20:21] op_sel_hi:[0,1,1]
	v_pk_fma_f32 v[20:21], v[32:33], v[38:39], v[22:23] op_sel_hi:[0,1,1]
	v_pk_fma_f32 v[22:23], v[32:33], v[54:55], v[24:25] op_sel_hi:[0,1,1]
	v_pk_fma_f32 v[24:25], v[32:33], v[40:41], v[26:27] op_sel_hi:[0,1,1]
	v_pk_fma_f32 v[26:27], v[32:33], v[56:57], v[28:29] op_sel_hi:[0,1,1]
	v_pk_fma_f32 v[28:29], v[32:33], v[42:43], v[30:31] op_sel_hi:[0,1,1]
	ds_read2st64_b32 v[30:31], v164 offset0:160 offset1:168
	s_waitcnt lgkmcnt(1)
	v_pk_fma_f32 v[10:11], v[10:11], v[70:71], v[2:3] op_sel_hi:[1,0,1]
	ds_read2st64_b32 v[2:3], v164 offset0:240 offset1:248
	v_lshlrev_b32_e32 v38, 16, v46
	v_and_b32_e32 v39, 0xffff0000, v46
	s_waitcnt lgkmcnt(1)
	v_pk_fma_f32 v[4:5], v[4:5], v[70:71], v[30:31] op_sel_hi:[1,0,1]
	v_lshlrev_b32_e32 v30, 16, v47
	v_and_b32_e32 v31, 0xffff0000, v47
	ds_read2st64_b32 v[46:47], v164 offset0:224 offset1:232
	s_waitcnt lgkmcnt(1)
	v_pk_fma_f32 v[14:15], v[14:15], v[70:71], v[2:3] op_sel_hi:[1,0,1]
	v_lshlrev_b64 v[2:3], 11, v[156:157]
	v_lshl_add_u64 v[2:3], s[2:3], 0, v[2:3]
	ds_read2st64_b32 v[40:41], v164 offset0:192 offset1:200
	s_waitcnt lgkmcnt(1)
	v_pk_fma_f32 v[12:13], v[12:13], v[70:71], v[46:47] op_sel_hi:[1,0,1]
	v_lshl_add_u64 v[46:47], v[2:3], 0, s[80:81]
	v_cvt_pk_bf16_f32 v0, v0, v1
	v_cvt_pk_bf16_f32 v1, v16, v17
	v_cvt_pk_bf16_f32 v2, v18, v19
	v_cvt_pk_bf16_f32 v3, v20, v21
	v_lshlrev_b32_e32 v16, 4, v190
	v_mov_b32_e32 v17, v215
	v_permlane32_swap_b32_e32 v0, v2
	v_permlane32_swap_b32_e32 v1, v3
	v_lshl_add_u64 v[16:17], v[46:47], 0, v[16:17]
	global_store_dwordx4 v[16:17], v[0:3], off offset:1024
	v_cndmask_b32_e64 v18, 48, 32, vcc
	v_mov_b32_e32 v19, v215
	v_cvt_pk_bf16_f32 v0, v22, v23
	v_cvt_pk_bf16_f32 v1, v24, v25
	v_cvt_pk_bf16_f32 v2, v26, v27
	v_cvt_pk_bf16_f32 v3, v28, v29
	v_lshlrev_b32_e32 v58, 16, v44
	v_and_b32_e32 v59, 0xffff0000, v44
	v_lshlrev_b32_e32 v44, 16, v45
	v_and_b32_e32 v45, 0xffff0000, v45
	v_permlane32_swap_b32_e32 v0, v2
	v_permlane32_swap_b32_e32 v1, v3
	v_lshl_add_u64 v[18:19], v[46:47], 0, v[18:19]
	global_store_dwordx4 v[18:19], v[0:3], off offset:1024
	v_pk_fma_f32 v[4:5], v[32:33], v[38:39], v[4:5] op_sel_hi:[0,1,1]
	v_pk_fma_f32 v[6:7], v[32:33], v[30:31], v[6:7] op_sel_hi:[0,1,1]
	v_pk_fma_f32 v[0:1], v[32:33], v[58:59], v[50:51] op_sel_hi:[0,1,1]
	v_pk_fma_f32 v[2:3], v[32:33], v[44:45], v[36:37] op_sel_hi:[0,1,1]
	v_lshlrev_b32_e32 v42, 16, v48
	v_and_b32_e32 v43, 0xffff0000, v48
	s_waitcnt lgkmcnt(0)
; __device__ __forceinline__ unsigned cvtpk(float lo, float hi) { f32x2 v = {lo, hi}; bf16x2_t b = __builtin_convertvector(v, bf16x2_t); return __builtin_bit_cast(unsigned, b); }
; __device__ __forceinline__ float oload(LAS unsigned char* lds, int tid, int i) { return ((LAS float*)(lds + OSAVE_OFF) + tid)[i * 512]; }
; __device__ __forceinline__ void store_o_bf16(bf16_t* dst, const f32x16 (&o)[2], int hi) {
; #pragma unroll
;     for (int dh = 0; dh < 2; ++dh)
; #pragma unroll
;         for (int ap = 0; ap < 2; ++ap) {
;             const int a0 = 2 * ap, a1 = a0 + 1;
;             unsigned x0 = cvtpk(o[dh][4 * a0], o[dh][4 * a0 + 1]), x1 = cvtpk(o[dh][4 * a0 + 2], o[dh][4 * a0 + 3]);
;             unsigned y0 = cvtpk(o[dh][4 * a1], o[dh][4 * a1 + 1]), y1 = cvtpk(o[dh][4 * a1 + 2], o[dh][4 * a1 + 3]);
;             const auto r0 = __builtin_amdgcn_permlane32_swap(x0, y0, false, false);
;             const auto r1 = __builtin_amdgcn_permlane32_swap(x1, y1, false, false);
;             const u32x4 w = {r0[0], r1[0], r0[1], r1[1]};
;             *(u32x4*)(dst + 32 * dh + 8 * (hi ? a1 : a0)) = w;
;         }
; }
; __device__ __forceinline__ void attn_phase(LAS unsigned char* lds, int* counter, const bf16_t* __restrict__ P, const bf16_t* __restrict__ Qm, const bf16_t* __restrict__ Kmla, ...
;     ...
;                     const u32x2 raw = *(const u32x2*)(oc + 32 * dh + 8 * a + 4 * hi);
;                     const float c0 = __uint_as_float(raw.x << 16), c1 = __uint_as_float(raw.x & 0xffff0000u), c2 = __uint_as_float(raw.y << 16), c3 = __uint_as_float(raw.y & 0xffff0000u);
;                     o[dh][4 * a + 0] = o[dh][4 * a + 0] * sc2 + oload(lds, tid, 16 * dh + 4 * a + 0) + g0 * c0;
;                     o[dh][4 * a + 1] = o[dh][4 * a + 1] * sc2 + oload(lds, tid, 16 * dh + 4 * a + 1) + g0 * c1;
;                     o[dh][4 * a + 2] = o[dh][4 * a + 2] * sc2 + oload(lds, tid, 16 * dh + 4 * a + 2) + g0 * c2;
;                     o[dh][4 * a + 3] = o[dh][4 * a + 3] * sc2 + oload(lds, tid, 16 * dh + 4 * a + 3) + g0 * c3;
;                 }
;             store_o_bf16(Omix + row * DM + 512 + head * 64, o, hi);
	v_pk_fma_f32 v[8:9], v[8:9], v[70:71], v[40:41] op_sel_hi:[1,0,1]
	v_lshlrev_b32_e32 v40, 16, v49
	v_and_b32_e32 v41, 0xffff0000, v49
	v_lshlrev_b32_e32 v48, 16, v34
	v_and_b32_e32 v49, 0xffff0000, v34
	v_lshlrev_b32_e32 v34, 16, v35
	v_and_b32_e32 v35, 0xffff0000, v35
	v_cvt_pk_bf16_f32 v0, v0, v1
	v_cvt_pk_bf16_f32 v1, v2, v3
	v_cvt_pk_bf16_f32 v2, v4, v5
	v_cvt_pk_bf16_f32 v3, v6, v7
	v_pk_fma_f32 v[8:9], v[32:33], v[42:43], v[8:9] op_sel_hi:[0,1,1]
	v_pk_fma_f32 v[10:11], v[32:33], v[40:41], v[10:11] op_sel_hi:[0,1,1]
	v_pk_fma_f32 v[12:13], v[32:33], v[48:49], v[12:13] op_sel_hi:[0,1,1]
	v_pk_fma_f32 v[14:15], v[32:33], v[34:35], v[14:15] op_sel_hi:[0,1,1]
	v_permlane32_swap_b32_e32 v0, v2
	v_permlane32_swap_b32_e32 v1, v3
	global_store_dwordx4 v[16:17], v[0:3], off offset:1088
	s_mov_b64 s[2:3], 0
	s_nop 0
	v_cvt_pk_bf16_f32 v0, v8, v9
	v_cvt_pk_bf16_f32 v1, v10, v11
	v_cvt_pk_bf16_f32 v2, v12, v13
	v_cvt_pk_bf16_f32 v3, v14, v15
	s_nop 0
	v_permlane32_swap_b32_e32 v0, v2
	v_permlane32_swap_b32_e32 v1, v3
	global_store_dwordx4 v[18:19], v[0:3], off offset:1088
; __device__ __forceinline__ int make_tid(int wave0) { int t = wave0 * 64 + (int)__builtin_amdgcn_mbcnt_hi(~0u, __builtin_amdgcn_mbcnt_lo(~0u, 0u)); asm volatile("" : "+v"(t)); return t; }
; #define AT_DMAV(t) do { const int t_ = AT_CL(t); LAS unsigned char* d_ = lds + (t_ % 3) * SLOT + KSL; \
;         __builtin_amdgcn_global_load_lds((const GAS unsigned*)(vsrc + (size_t)t_ * 64 * vs), (LAS unsigned*)(d_ + wid * 1024), 16, 0, 0); } while (0)
; template <int DQK, int MODE> ...
;     ...
;     const int tid = make_tid(wave0), lane = tid & 63, r32 = lane & 31, hi = lane >> 5;
;     const int wid = wave0;
;     const int tw0 = t0 + 32 * wid, tq = tw0 + r32;
;     bf16x8 qf[NDS];
; #pragma unroll
;     for (int ds = 0; ds < NDS; ++ds) qf[ds] = *(const bf16x8*)(Qp + (size_t)tq * qs + 16 * ds + 8 * hi);
;     int kt_lo = 0; const int kt_hi = (t0 >> 6) + 3;
;     if (MODE == 1) { const int lo = t0 - 511; kt_lo = lo > 0 ? (lo >> 6) : 0; }
;     unsigned long long selm = 0ull; if (MODE == 2) selm = selp[tq];
;     const int kc0 = wid % CPR, kc1 = (8 + (wid & 3)) % CPR;
;     const bf16_t* ksrc0 = Kp + (size_t)lane * ks + kc0 * 8;
;     const bf16_t* ksrc1 = Kp + (size_t)lane * ks + kc1 * 8;
;     const bf16_t* vsrc = Vp + (size_t)(16 * (wid & 3) + (lane >> 2)) * vs + (wid >> 2) * 32 + (lane & 3) * 8;
;     ...
;     o[0] = f32x16{}; o[1] = f32x16{};
;     float m_run = 0.f, l_run = 0.f; bool init = false;
;     f32x16 negm = f32x16{}; asm volatile("" : "+v"(negm));
;     f32x16 pa0 = f32x16{}, pa1 = f32x16{}, pb0 = f32x16{}, pb1 = f32x16{};
;     bf16x8 kf[2 * NDS];
;     AT_DMAK(kt_lo); AT_DMAV(kt_lo); AT_DMAK(kt_lo + 1); AT_DMAK(kt_lo + 2); AT_DMAV(kt_lo + 1);
;     if (NKW > 1) AT_WAITBAR(3); else AT_WAITBAR(2);
;     { AT_KFRAG(kt_lo); asm volatile("s_waitcnt lgkmcnt(0)\n\ts_barrier" ::: "memory");
;       const float b_ = AT_BIAS(kt_lo); AT_QKM(pa0, pa1, AT_SPLAT(b_)); }
; __device__ __forceinline__ void attn_phase(LAS unsigned char* lds, int* counter, const bf16_t* __restrict__ P, const bf16_t* __restrict__ Qm, const bf16_t* __restrict__ Kmla, ...
;     ...
;             const int b = (r - 32) >> 2, h = (r - 32) & 3;
;             const size_t rb = (size_t)b * SEQ;
;             attn_pass<96, 0>(lds, Qm + rb * 384 + h * 96, 384, Kmla + rb * 384 + h * 96, 384, Vmla + rb * 256 + h * 64, 256, t0, nullptr, o, linv, wave0);
.LBB0_713:
	s_and_b64 vcc, exec, s[2:3]
	s_cbranch_vccz .LBB0_727
	s_sub_i32 s2, s41, 32
	s_lshr_b32 s16, s2, 2
	s_and_b32 s19, s41, 3
	s_mul_i32 s5, s16, 0x300000
	s_mul_hi_u32 s4, s16, 0x300000
	s_add_u32 s2, s26, s5
	s_addc_u32 s3, s27, s4
	s_mul_i32 s6, s19, 0xc0
	s_add_u32 s2, s2, s6
	v_mov_b32_e32 v8, v246
	s_addc_u32 s3, s3, 0
	v_mov_b64_e32 v[0:1], s[2:3]
	v_and_b32_e32 v9, 31, v8
	v_bfe_u32 v10, v8, 5, 1
	v_or_b32_e32 v2, s39, v9
	v_mad_u64_u32 v[0:1], s[2:3], v2, s73, v[0:1]
	v_lshlrev_b32_e32 v2, 4, v10
	v_mov_b32_e32 v3, v215
	v_lshl_add_u64 v[0:1], v[0:1], 0, v[2:3]
	global_load_dwordx4 v[112:115], v[0:1], off
	global_load_dwordx4 v[116:119], v[0:1], off offset:32
	global_load_dwordx4 v[120:123], v[0:1], off offset:64
	global_load_dwordx4 v[124:127], v[0:1], off offset:96
	global_load_dwordx4 v[128:131], v[0:1], off offset:128
	global_load_dwordx4 v[132:135], v[0:1], off offset:160
	s_add_u32 s5, s28, s5
	s_addc_u32 s7, s29, s4
	v_and_b32_e32 v4, 63, v8
	s_add_u32 s4, s5, s6
	v_mul_u32_u24_e32 v0, 0x180, v4
	s_addc_u32 s5, s7, 0
	v_lshlrev_b32_e32 v0, 1, v0
	v_mov_b32_e32 v1, v215
	v_readlane_b32 s2, v254, 12
	v_lshl_add_u64 v[0:1], s[4:5], 0, v[0:1]
	s_mov_b32 s4, s2
	v_readlane_b32 s3, v254, 13
	v_writelane_b32 v254, s4, 12
	s_mov_b32 s3, s81
	v_lshl_add_u64 v[184:185], v[0:1], 0, s[2:3]
	v_writelane_b32 v254, s5, 13
	s_mov_b32 s17, s81
	v_readlane_b32 s2, v254, 14
	v_readlane_b32 s3, v254, 15
	s_lshl_b64 s[6:7], s[16:17], 21
	s_mov_b32 s3, s81
	s_add_u32 s6, s30, s6
	v_lshl_add_u64 v[186:187], v[0:1], 0, s[2:3]
	v_lshlrev_b32_e32 v0, 6, v8
	s_addc_u32 s7, s31, s7
	s_lshl_b32 s18, s19, 6
	s_lshl_b32 s19, s19, 7
	v_and_b32_e32 v0, 0xf00, v0
	s_add_u32 s6, s6, s19
	s_mov_b32 s4, s2
	v_or_b32_e32 v0, s62, v0
	s_addc_u32 s7, s7, 0
	v_writelane_b32 v254, s4, 14
	v_lshlrev_b32_e32 v0, 1, v0
	v_mov_b32_e32 v1, v215
	v_lshlrev_b32_e32 v2, 3, v8
	s_add_i32 s2, s63, 0
	v_writelane_b32 v254, s5, 15
	v_lshl_add_u64 v[0:1], s[6:7], 0, v[0:1]
	s_lshl_b32 s80, s60, 1
	v_and_b32_e32 v11, 24, v2
	v_mov_b32_e32 v32, v215
	v_mov_b32_e32 v33, v215
	v_mov_b32_e32 v34, v215
	v_mov_b32_e32 v35, v215
	v_mov_b32_e32 v36, v215
	v_mov_b32_e32 v37, v215
	v_mov_b32_e32 v38, v215
	v_mov_b32_e32 v39, v215
	v_mov_b32_e32 v40, v215
	v_mov_b32_e32 v41, v215
	v_mov_b32_e32 v42, v215
	v_mov_b32_e32 v43, v215
	v_mov_b32_e32 v44, v215
	v_mov_b32_e32 v45, v215
	v_mov_b32_e32 v46, v215
	v_mov_b32_e32 v47, v215
	s_mov_b32 m0, s2
	s_add_i32 s3, s75, 0
	v_lshl_add_u64 v[0:1], v[0:1], 0, s[80:81]
	v_lshlrev_b32_e32 v2, 1, v11
	global_load_lds_dwordx4 v[184:185], off
	s_mov_b32 m0, s3
	v_readlane_b32 s4, v254, 8
	v_lshl_add_u64 v[188:189], v[0:1], 0, v[2:3]
	global_load_lds_dwordx4 v[186:187], off
	s_mov_b32 m0, s4
	s_mov_b64 s[4:5], 0xc000
	global_load_lds_dwordx4 v[188:189], off
	v_lshl_add_u64 v[0:1], v[184:185], 0, s[4:5]
	s_add_i32 m0, s2, 0x5000
	v_lshlrev_b32_e32 v192, 10, v10
	global_load_lds_dwordx4 v[0:1], off
	v_lshl_add_u64 v[0:1], v[186:187], 0, s[4:5]
	s_add_i32 m0, s3, 0x5000
	s_mov_b64 s[4:5], 0x18000
	global_load_lds_dwordx4 v[0:1], off
	v_lshl_add_u64 v[0:1], v[184:185], 0, s[4:5]
	s_add_i32 m0, s2, 0xa000
	v_lshlrev_b32_e32 v193, 4, v9
	global_load_lds_dwordx4 v[0:1], off
	v_lshl_add_u64 v[0:1], v[186:187], 0, s[4:5]
	s_add_i32 m0, s3, 0xa000
	s_mov_b64 s[2:3], 0x8000
	global_load_lds_dwordx4 v[0:1], off
	v_lshl_add_u64 v[0:1], v[188:189], 0, s[2:3]
	s_add_i32 m0, s33, 0x8000
	v_add3_u32 v194, 0, v192, v193
	global_load_lds_dwordx4 v[0:1], off
	s_waitcnt vmcnt(3) lgkmcnt(0)
	s_barrier
	ds_read_b128 v[0:3], v194
	ds_read_b128 v[4:7], v194 offset:512
	s_waitcnt vmcnt(3) lgkmcnt(0)
	v_mfma_f32_32x32x16_bf16 v[48:63], v[0:3], v[112:115], 0
	s_lshr_b32 s2, s40, 6
	v_mov_b32_e32 v197, 0
	s_mov_b32 s19, 4
	s_mov_b32 s20, 1
	s_mov_b32 s21, 0
	s_or_b32 s22, s2, 3
	s_mov_b64 s[2:3], 0
	v_mfma_f32_32x32x16_bf16 v[64:79], v[4:7], v[112:115], 0
	ds_read_b128 v[0:3], v194 offset:2048
	ds_read_b128 v[4:7], v194 offset:2560
	s_movk_i32 s23, 0x7f
	v_mov_b32_e32 v198, 0
	v_mov_b32_e32 v12, v197
	v_mov_b32_e32 v13, v197
	v_mov_b32_e32 v14, v197
	v_mov_b32_e32 v15, v197
	s_waitcnt lgkmcnt(1)
	v_mfma_f32_32x32x16_bf16 v[48:63], v[0:3], v[116:119], v[48:63]
	v_mov_b32_e32 v16, v197
	v_mov_b32_e32 v17, v197
	v_mov_b32_e32 v18, v197
	v_mov_b32_e32 v19, v197
	v_mov_b32_e32 v20, v197
	v_mov_b32_e32 v21, v197
	v_mov_b32_e32 v22, v197
	s_waitcnt lgkmcnt(0)
	v_mfma_f32_32x32x16_bf16 v[64:79], v[4:7], v[116:119], v[64:79]
	ds_read_b128 v[0:3], v194 offset:4096
	ds_read_b128 v[4:7], v194 offset:4608
	v_mov_b32_e32 v23, v197
	v_mov_b32_e32 v24, v197
	v_mov_b32_e32 v25, v197
	v_mov_b32_e32 v26, v197
	v_mov_b32_e32 v27, v197
	v_mov_b32_e32 v28, v197
	s_waitcnt lgkmcnt(1)
	v_mfma_f32_32x32x16_bf16 v[48:63], v[0:3], v[120:123], v[48:63]
	v_mov_b32_e32 v29, v197
	v_mov_b32_e32 v30, v197
	v_mov_b32_e32 v31, v197
	s_waitcnt lgkmcnt(0)
	v_mfma_f32_32x32x16_bf16 v[64:79], v[4:7], v[120:123], v[64:79]
	ds_read_b128 v[0:3], v194 offset:6144
	ds_read_b128 v[4:7], v194 offset:6656
	s_waitcnt lgkmcnt(1)
	v_mfma_f32_32x32x16_bf16 v[48:63], v[0:3], v[124:127], v[48:63]
	s_waitcnt lgkmcnt(0)
	v_mfma_f32_32x32x16_bf16 v[64:79], v[4:7], v[124:127], v[64:79]
	ds_read_b128 v[0:3], v194 offset:8192
	ds_read_b128 v[4:7], v194 offset:8704
	s_waitcnt lgkmcnt(1)
	v_mfma_f32_32x32x16_bf16 v[48:63], v[0:3], v[128:131], v[48:63]
	s_waitcnt lgkmcnt(0)
	v_mfma_f32_32x32x16_bf16 v[64:79], v[4:7], v[128:131], v[64:79]
	ds_read_b128 v[0:3], v194 offset:10240
	ds_read_b128 v[4:7], v194 offset:10752
	s_waitcnt lgkmcnt(0)
	s_barrier
	s_waitcnt lgkmcnt(1)
	v_mfma_f32_32x32x16_bf16 v[48:63], v[0:3], v[132:135], v[48:63]
	v_lshlrev_b32_e32 v2, 4, v8
	v_lshlrev_b32_e32 v0, 1, v8
	v_and_b32_e32 v2, 0xc0, v2
	v_and_b32_e32 v0, 32, v0
	v_lshl_or_b32 v2, v10, 8, v2
	v_or3_b32 v0, v2, v0, v11
	v_lshlrev_b32_e32 v1, 2, v10
	s_waitcnt lgkmcnt(0)
	v_mfma_f32_32x32x16_bf16 v[64:79], v[4:7], v[132:135], v[64:79]
	v_add_u32_e32 v195, 0, v0
	v_add_u32_e32 v0, s39, v9
	v_sub_u32_e32 v196, v0, v1
	v_mov_b32_e32 v0, 0
	v_mov_b32_e32 v1, v197
	v_mov_b32_e32 v2, v197
	v_mov_b32_e32 v3, v197
	v_mov_b32_e32 v4, v197
	v_mov_b32_e32 v5, v197
	v_mov_b32_e32 v6, v197
	v_mov_b32_e32 v7, v197
	v_mov_b32_e32 v8, v197
	v_mov_b32_e32 v9, v197
	v_mov_b32_e32 v10, v197
	v_mov_b32_e32 v11, v197
	v_readfirstlane_b32 s86, v184
	v_readfirstlane_b32 s87, v185
	v_readfirstlane_b32 s98, v188
	v_readfirstlane_b32 s99, v189
	s_nop 1
	v_subrev_u32_e32 v200, s86, v184
	v_subrev_u32_e32 v201, s86, v186
	v_subrev_u32_e32 v202, s98, v188
	s_branch .LBB0_717

.LBB0_717:
	s_add_i32 s4, s19, -1
	s_min_u32 s44, s4, s22
	s_mul_hi_u32 s4, s44, 0x55555556
	s_mul_i32 s4, s4, 3
	s_sub_i32 s4, s44, s4
	s_mulk_i32 s4, 0x5000
	s_add_i32 s42, s19, -2
	s_add_i32 s45, s4, 0
	s_min_u32 s4, s42, s22
	s_mul_hi_u32 s5, s4, 0x55555556
	s_mul_i32 s5, s5, 3
	s_sub_i32 s5, s4, s5
	s_mul_i32 s80, s44, 0xc000
	s_mulk_i32 s5, 0x5000
	v_add_u32_e32 v80, s80, v200
	s_add_i32 m0, s45, s63
	s_add_i32 s43, s5, 0
	global_load_lds_dwordx4 v80, s[86:87]
	v_add_u32_e32 v80, s80, v201
	s_add_i32 m0, s45, s75
	s_lshl_b32 s80, s4, 15
	s_add_i32 s4, s43, s95
	global_load_lds_dwordx4 v80, s[86:87]
	v_add_u32_e32 v80, s80, v202
	s_add_i32 m0, s4, 0x3000
	s_sub_i32 s4, s23, 64
	global_load_lds_dwordx4 v80, s[98:99]
	s_cmp_le_u32 s4, s39
	s_sub_i32 s5, s4, 94
	s_cmp_gt_i32 s5, s39
	s_cbranch_scc1 .Ltsk717_d1
	s_cmp_le_u32 s4, s39
	s_cbranch_scc1 .LBB0_719
	v_cmp_lt_i32_e64 s[4:5], -1, v196
	v_cmp_lt_i32_e64 s[6:7], 31, v196
	v_cmp_lt_i32_e32 vcc, 0, v196
	v_cndmask_b32_e64 v48, v249, v48, s[4:5]
	v_cmp_lt_i32_e64 s[4:5], 32, v196
	v_cndmask_b32_e64 v64, v249, v64, s[6:7]
	v_cmp_lt_i32_e64 s[6:7], 1, v196
	v_cndmask_b32_e32 v49, v249, v49, vcc
	v_cmp_lt_i32_e32 vcc, 33, v196
	v_cndmask_b32_e64 v65, v249, v65, s[4:5]
	v_cmp_lt_i32_e64 s[4:5], 2, v196
	v_cndmask_b32_e64 v50, v249, v50, s[6:7]
	v_cmp_lt_i32_e64 s[6:7], 34, v196
	v_cndmask_b32_e32 v66, v249, v66, vcc
	v_cmp_lt_i32_e32 vcc, 7, v196
	v_cndmask_b32_e64 v51, v249, v51, s[4:5]
	v_cmp_lt_i32_e64 s[4:5], 39, v196
	v_cndmask_b32_e64 v67, v249, v67, s[6:7]
	v_cmp_lt_i32_e64 s[6:7], 8, v196
	v_cndmask_b32_e32 v52, v249, v52, vcc
	v_cmp_lt_i32_e32 vcc, 40, v196
	v_cndmask_b32_e64 v68, v249, v68, s[4:5]
	v_cmp_lt_i32_e64 s[4:5], 9, v196
	v_cndmask_b32_e64 v53, v249, v53, s[6:7]
	v_cmp_lt_i32_e64 s[6:7], 41, v196
	v_cndmask_b32_e32 v69, v249, v69, vcc
	v_cmp_lt_i32_e32 vcc, 10, v196
	v_cndmask_b32_e64 v54, v249, v54, s[4:5]
	v_cmp_lt_i32_e64 s[4:5], 42, v196
	v_cndmask_b32_e64 v70, v249, v70, s[6:7]
	v_cmp_lt_i32_e64 s[6:7], 15, v196
	v_cndmask_b32_e32 v55, v249, v55, vcc
	v_cmp_lt_i32_e32 vcc, 47, v196
	v_cndmask_b32_e64 v71, v249, v71, s[4:5]
	v_cmp_lt_i32_e64 s[4:5], 16, v196
	v_cndmask_b32_e64 v56, v249, v56, s[6:7]
	v_cmp_lt_i32_e64 s[6:7], 48, v196
	v_cndmask_b32_e32 v72, v249, v72, vcc
	v_cmp_lt_i32_e32 vcc, 17, v196
	v_cndmask_b32_e64 v57, v249, v57, s[4:5]
	v_cmp_lt_i32_e64 s[4:5], 49, v196
	v_cndmask_b32_e64 v73, v249, v73, s[6:7]
	v_cmp_lt_i32_e64 s[6:7], 18, v196
	v_cndmask_b32_e32 v58, v249, v58, vcc
	v_cmp_lt_i32_e32 vcc, 50, v196
	v_cndmask_b32_e64 v74, v249, v74, s[4:5]
	v_cmp_lt_i32_e64 s[4:5], 23, v196
	v_cndmask_b32_e64 v59, v249, v59, s[6:7]
	v_cmp_lt_i32_e64 s[6:7], 55, v196
	v_cndmask_b32_e32 v75, v249, v75, vcc
	v_cmp_lt_i32_e32 vcc, 24, v196
	v_cndmask_b32_e64 v60, v249, v60, s[4:5]
	v_cmp_lt_i32_e64 s[4:5], 56, v196
	v_cndmask_b32_e64 v76, v249, v76, s[6:7]
	v_cmp_lt_i32_e64 s[6:7], 25, v196
	v_cndmask_b32_e32 v61, v249, v61, vcc
	v_cmp_lt_i32_e32 vcc, 57, v196
	v_cndmask_b32_e64 v77, v249, v77, s[4:5]
	v_cmp_lt_i32_e64 s[4:5], 26, v196
	v_cndmask_b32_e64 v62, v249, v62, s[6:7]
	v_cmp_lt_i32_e64 s[6:7], 58, v196
	v_cndmask_b32_e32 v78, v249, v78, vcc
	s_nop 0
	v_cndmask_b32_e64 v63, v249, v63, s[4:5]
	s_nop 0
	v_cndmask_b32_e64 v79, v249, v79, s[6:7]

.Ltsk717_s2:
	s_min_u32 s4, s19, s22
	s_mul_hi_u32 s5, s4, 0x55555556
	s_mul_i32 s5, s5, 3
	s_sub_i32 s5, s4, s5
	s_mulk_i32 s5, 0x5000
	s_add_i32 s5, s5, 0
	s_mul_i32 s80, s4, 0xc000
	v_add_u32_e32 v48, s80, v200
	s_add_i32 m0, s5, s63
	s_add_i32 s4, s45, s95
	global_load_lds_dwordx4 v48, s[86:87]
	v_add_u32_e32 v48, s80, v201
	s_add_i32 m0, s5, s75
	s_lshl_b32 s80, s44, 15
	global_load_lds_dwordx4 v48, s[86:87]
	v_add_u32_e32 v48, s80, v202
	s_add_i32 m0, s4, 0x3000
	s_cmp_le_u32 s23, s39
	global_load_lds_dwordx4 v48, s[98:99]
	s_sub_i32 s5, s23, 94
	s_cmp_gt_i32 s5, s39
	s_cbranch_scc1 .Ltsk717_d2
	s_cmp_le_u32 s23, s39
	s_cbranch_scc1 .LBB0_724
	v_subrev_u32_e32 v48, 64, v196
	v_cmp_lt_i32_e64 s[4:5], -1, v48
	v_cmp_lt_i32_e64 s[6:7], 31, v48
	v_cmp_lt_i32_e32 vcc, 0, v48
	v_cndmask_b32_e64 v96, v249, v96, s[4:5]
	v_cmp_lt_i32_e64 s[4:5], 32, v48
	v_cndmask_b32_e64 v80, v249, v80, s[6:7]
	v_cmp_lt_i32_e64 s[6:7], 1, v48
	v_cndmask_b32_e32 v97, v249, v97, vcc
	v_cmp_lt_i32_e32 vcc, 33, v48
	v_cndmask_b32_e64 v81, v249, v81, s[4:5]
	v_cmp_lt_i32_e64 s[4:5], 2, v48
	v_cndmask_b32_e64 v98, v249, v98, s[6:7]
	v_cmp_lt_i32_e64 s[6:7], 34, v48
	v_cndmask_b32_e32 v82, v249, v82, vcc
	v_cmp_lt_i32_e32 vcc, 7, v48
	v_cndmask_b32_e64 v99, v249, v99, s[4:5]
	v_cmp_lt_i32_e64 s[4:5], 39, v48
	v_cndmask_b32_e64 v83, v249, v83, s[6:7]
	v_cmp_lt_i32_e64 s[6:7], 8, v48
	v_cndmask_b32_e32 v100, v249, v100, vcc
	v_cmp_lt_i32_e32 vcc, 40, v48
	v_cndmask_b32_e64 v84, v249, v84, s[4:5]
	v_cmp_lt_i32_e64 s[4:5], 9, v48
	v_cndmask_b32_e64 v101, v249, v101, s[6:7]
	v_cmp_lt_i32_e64 s[6:7], 41, v48
	v_cndmask_b32_e32 v85, v249, v85, vcc
	v_cmp_lt_i32_e32 vcc, 10, v48
	v_cndmask_b32_e64 v102, v249, v102, s[4:5]
	v_cmp_lt_i32_e64 s[4:5], 42, v48
	v_cndmask_b32_e64 v86, v249, v86, s[6:7]
	v_cmp_lt_i32_e64 s[6:7], 15, v48
	v_cndmask_b32_e32 v103, v249, v103, vcc
	v_cmp_lt_i32_e32 vcc, 47, v48
	v_cndmask_b32_e64 v87, v249, v87, s[4:5]
	v_cmp_lt_i32_e64 s[4:5], 16, v48
	v_cndmask_b32_e64 v104, v249, v104, s[6:7]
	v_cmp_lt_i32_e64 s[6:7], 48, v48
	v_cndmask_b32_e32 v88, v249, v88, vcc
	v_cmp_lt_i32_e32 vcc, 17, v48
	v_cndmask_b32_e64 v105, v249, v105, s[4:5]
	v_cmp_lt_i32_e64 s[4:5], 49, v48
	v_cndmask_b32_e64 v89, v249, v89, s[6:7]
	v_cmp_lt_i32_e64 s[6:7], 18, v48
	v_cndmask_b32_e32 v106, v249, v106, vcc
	v_cmp_lt_i32_e32 vcc, 50, v48
	v_cndmask_b32_e64 v90, v249, v90, s[4:5]
	v_cmp_lt_i32_e64 s[4:5], 23, v48
	v_cndmask_b32_e64 v107, v249, v107, s[6:7]
	v_cmp_lt_i32_e64 s[6:7], 55, v48
	v_cndmask_b32_e32 v91, v249, v91, vcc
	v_cmp_lt_i32_e32 vcc, 24, v48
	v_cndmask_b32_e64 v108, v249, v108, s[4:5]
	v_cmp_lt_i32_e64 s[4:5], 56, v48
	v_cndmask_b32_e64 v92, v249, v92, s[6:7]
	v_cmp_lt_i32_e64 s[6:7], 25, v48
	v_cndmask_b32_e32 v109, v249, v109, vcc
	v_cmp_lt_i32_e32 vcc, 57, v48
	v_cndmask_b32_e64 v93, v249, v93, s[4:5]
	v_cmp_lt_i32_e64 s[4:5], 26, v48
	v_cndmask_b32_e64 v110, v249, v110, s[6:7]
	v_cmp_lt_i32_e64 s[6:7], 58, v48
	v_cndmask_b32_e32 v94, v249, v94, vcc
	s_nop 0
	v_cndmask_b32_e64 v111, v249, v111, s[4:5]
	s_nop 0
	v_cndmask_b32_e64 v95, v249, v95, s[6:7]

; __device__ __forceinline__ float sum32x(float v) { auto rr = __builtin_amdgcn_permlane32_swap(__float_as_uint(v), __float_as_uint(v), false, false); return __uint_as_float(rr[0]) + __uint_as_float(rr[1]); }
; template <int DQK, int MODE> ...
;     ...
;     const float lt = sum32x(l_run);
;     linv = lt > 0.f ? 1.0f / lt : 0.f;
; __device__ __forceinline__ void attn_phase(LAS unsigned char* lds, int* counter, const bf16_t* __restrict__ P, const bf16_t* __restrict__ Qm, const bf16_t* __restrict__ Kmla, ...
;     ...
;             const int b = (r - 32) >> 2, h = (r - 32) & 3;
;             const size_t rb = (size_t)b * SEQ;
;             attn_pass<96, 0>(lds, Qm + rb * 384 + h * 96, 384, Kmla + rb * 384 + h * 96, 384, Vmla + rb * 256 + h * 64, 256, t0, nullptr, o, linv, wave0);
; #pragma unroll
;             for (int i = 0; i < 16; ++i) { o[0][i] *= linv; o[1][i] *= linv; }
;             store_o_bf16(Omix + (rb + tq) * DM + h * 64, o, hi);
.LBB0_726:
	v_readlane_b32 s86, v254, 37
	v_readlane_b32 s87, v254, 38
	v_mov_b32_e32 v32, v198
	s_nop 1
	v_permlane32_swap_b32_e32 v198, v32
	v_add_f32_e32 v32, v198, v32
	v_div_scale_f32 v33, s[2:3], v32, v32, 1.0
	v_rcp_f32_e32 v34, v33
	s_lshl_b64 s[2:3], s[16:17], 23
	v_readlane_b32 s4, v254, 46
	v_readlane_b32 s5, v254, 47
	v_fma_f32 v35, -v33, v34, 1.0
	v_fmac_f32_e32 v34, v35, v34
	v_div_scale_f32 v35, vcc, 1.0, v32, 1.0
	v_mul_f32_e32 v36, v35, v34
	v_fma_f32 v37, -v33, v36, v35
	v_fmac_f32_e32 v36, v37, v34
	v_fma_f32 v33, -v33, v36, v35
	v_div_fmas_f32 v33, v33, v34, v36
	v_div_fixup_f32 v33, v33, v32, 1.0
	v_cmp_lt_f32_e32 vcc, 0, v32
	s_add_u32 s2, s4, s2
	s_addc_u32 s3, s5, s3
	v_cndmask_b32_e32 v32, 0, v33, vcc
	v_pk_mul_f32 v[0:1], v[0:1], v[32:33] op_sel_hi:[1,0]
	v_pk_mul_f32 v[16:17], v[16:17], v[32:33] op_sel_hi:[1,0]
	v_pk_mul_f32 v[2:3], v[2:3], v[32:33] op_sel_hi:[1,0]
	v_pk_mul_f32 v[18:19], v[18:19], v[32:33] op_sel_hi:[1,0]
	v_pk_mul_f32 v[4:5], v[4:5], v[32:33] op_sel_hi:[1,0]
	v_pk_mul_f32 v[20:21], v[20:21], v[32:33] op_sel_hi:[1,0]
	v_pk_mul_f32 v[6:7], v[6:7], v[32:33] op_sel_hi:[1,0]
	v_pk_mul_f32 v[22:23], v[22:23], v[32:33] op_sel_hi:[1,0]
	v_pk_mul_f32 v[8:9], v[8:9], v[32:33] op_sel_hi:[1,0]
	v_pk_mul_f32 v[24:25], v[24:25], v[32:33] op_sel_hi:[1,0]
	v_pk_mul_f32 v[10:11], v[10:11], v[32:33] op_sel_hi:[1,0]
	v_pk_mul_f32 v[26:27], v[26:27], v[32:33] op_sel_hi:[1,0]
	v_pk_mul_f32 v[12:13], v[12:13], v[32:33] op_sel_hi:[1,0]
	v_pk_mul_f32 v[28:29], v[28:29], v[32:33] op_sel_hi:[1,0]
	v_pk_mul_f32 v[14:15], v[14:15], v[32:33] op_sel_hi:[1,0]
	v_pk_mul_f32 v[30:31], v[30:31], v[32:33] op_sel_hi:[1,0]
	v_lshlrev_b64 v[32:33], 11, v[214:215]
	v_lshl_add_u64 v[32:33], s[2:3], 0, v[32:33]
	s_lshl_b32 s80, s18, 1
	v_lshl_add_u64 v[32:33], v[32:33], 0, s[80:81]
	v_cvt_pk_bf16_f32 v0, v0, v1
	v_cvt_pk_bf16_f32 v1, v2, v3
	v_cvt_pk_bf16_f32 v2, v4, v5
	v_cvt_pk_bf16_f32 v3, v6, v7
	v_lshlrev_b32_e32 v4, 4, v190
	v_mov_b32_e32 v5, v215
	v_permlane32_swap_b32_e32 v0, v2
	v_permlane32_swap_b32_e32 v1, v3
	v_lshl_add_u64 v[4:5], v[32:33], 0, v[4:5]
	v_cmp_eq_u32_e32 vcc, 0, v190
	s_waitcnt vmcnt(0) lgkmcnt(0)
	s_barrier
	global_store_dwordx4 v[4:5], v[0:3], off
	v_mov_b32_e32 v7, v215
	v_cndmask_b32_e64 v6, 48, 32, vcc
	v_cvt_pk_bf16_f32 v0, v8, v9
	v_cvt_pk_bf16_f32 v1, v10, v11
	v_cvt_pk_bf16_f32 v2, v12, v13
	v_cvt_pk_bf16_f32 v3, v14, v15
	s_nop 0
	v_permlane32_swap_b32_e32 v0, v2
	v_permlane32_swap_b32_e32 v1, v3
	v_lshl_add_u64 v[6:7], v[32:33], 0, v[6:7]
	global_store_dwordx4 v[6:7], v[0:3], off
	s_nop 1
	v_cvt_pk_bf16_f32 v0, v16, v17
	v_cvt_pk_bf16_f32 v1, v18, v19
	v_cvt_pk_bf16_f32 v2, v20, v21
	v_cvt_pk_bf16_f32 v3, v22, v23
	s_nop 0
	v_permlane32_swap_b32_e32 v0, v2
	v_permlane32_swap_b32_e32 v1, v3
	global_store_dwordx4 v[4:5], v[0:3], off offset:64
	s_nop 1
	v_cvt_pk_bf16_f32 v0, v24, v25
	v_cvt_pk_bf16_f32 v1, v26, v27
	v_cvt_pk_bf16_f32 v2, v28, v29
	v_cvt_pk_bf16_f32 v3, v30, v31
	s_nop 0
	v_permlane32_swap_b32_e32 v0, v2
	v_permlane32_swap_b32_e32 v1, v3
	global_store_dwordx4 v[6:7], v[0:3], off offset:64

; __device__ __forceinline__ int make_tid(int wave0) { int t = wave0 * 64 + (int)__builtin_amdgcn_mbcnt_hi(~0u, __builtin_amdgcn_mbcnt_lo(~0u, 0u)); asm volatile("" : "+v"(t)); return t; }
; #define AT_DMAV(t) do { const int t_ = AT_CL(t); LAS unsigned char* d_ = lds + (t_ % 3) * SLOT + KSL; \
;         __builtin_amdgcn_global_load_lds((const GAS unsigned*)(vsrc + (size_t)t_ * 64 * vs), (LAS unsigned*)(d_ + wid * 1024), 16, 0, 0); } while (0)
; template <int DQK, int MODE> ...
;     ...
;     const int tid = make_tid(wave0), lane = tid & 63, r32 = lane & 31, hi = lane >> 5;
;     const int wid = wave0;
;     const int tw0 = t0 + 32 * wid, tq = tw0 + r32;
;     bf16x8 qf[NDS];
; #pragma unroll
;     for (int ds = 0; ds < NDS; ++ds) qf[ds] = *(const bf16x8*)(Qp + (size_t)tq * qs + 16 * ds + 8 * hi);
;     int kt_lo = 0; const int kt_hi = (t0 >> 6) + 3;
;     if (MODE == 1) { const int lo = t0 - 511; kt_lo = lo > 0 ? (lo >> 6) : 0; }
;     unsigned long long selm = 0ull; if (MODE == 2) selm = selp[tq];
;     const int kc0 = wid % CPR, kc1 = (8 + (wid & 3)) % CPR;
;     const bf16_t* ksrc0 = Kp + (size_t)lane * ks + kc0 * 8;
;     const bf16_t* ksrc1 = Kp + (size_t)lane * ks + kc1 * 8;
;     const bf16_t* vsrc = Vp + (size_t)(16 * (wid & 3) + (lane >> 2)) * vs + (wid >> 2) * 32 + (lane & 3) * 8;
;     ...
;     o[0] = f32x16{}; o[1] = f32x16{};
;     float m_run = 0.f, l_run = 0.f; bool init = false;
;     f32x16 negm = f32x16{}; asm volatile("" : "+v"(negm));
;     f32x16 pa0 = f32x16{}, pa1 = f32x16{}, pb0 = f32x16{}, pb1 = f32x16{};
;     bf16x8 kf[2 * NDS];
;     AT_DMAK(kt_lo); AT_DMAV(kt_lo); AT_DMAK(kt_lo + 1); AT_DMAK(kt_lo + 2); AT_DMAV(kt_lo + 1);
;     if (NKW > 1) AT_WAITBAR(3); else AT_WAITBAR(2);
;     { AT_KFRAG(kt_lo); asm volatile("s_waitcnt lgkmcnt(0)\n\ts_barrier" ::: "memory");
;       const float b_ = AT_BIAS(kt_lo); AT_QKM(pa0, pa1, AT_SPLAT(b_)); }
; __device__ __forceinline__ void attn_phase(LAS unsigned char* lds, int* counter, const bf16_t* __restrict__ P, const bf16_t* __restrict__ Qm, const bf16_t* __restrict__ Kmla, ...
;     ...
;         if (r < 32) {
;             const int b = r >> 2, h = r & 3;
;             const bf16_t* Pb = P + (size_t)b * SEQ * NPJ;
;             attn_pass<32, 0>(lds, Pb + C_DQ + (2 * h) * 32, NPJ, Pb + C_DK + (2 * h) * 32, NPJ, Pb + C_DV + h * 64, NPJ, t0, nullptr, o, linv, wave0);
.LBB0_728:
	s_andn2_b64 vcc, exec, s[2:3]
	s_cbranch_vccnz .LBB0_668
	s_ashr_i32 s22, s41, 2
	s_mul_i32 s3, s22, 0x1400000
	v_readlane_b32 s4, v254, 48
	s_mul_hi_i32 s2, s22, 0x1400000
	v_readlane_b32 s5, v254, 49
	s_add_u32 s3, s4, s3
	s_addc_u32 s2, s5, s2
	s_lshl_b32 s4, s41, 6
	s_and_b32 s23, s4, 0xc0
	s_lshl_b32 s4, s23, 1
	s_add_u32 s16, s3, s4
	v_mov_b32_e32 v8, v246
	s_addc_u32 s17, s2, 0
	v_mov_b64_e32 v[0:1], s[16:17]
	v_and_b32_e32 v9, 31, v8
	v_bfe_u32 v10, v8, 5, 1
	v_or_b32_e32 v2, s39, v9
	v_mad_u64_u32 v[0:1], s[2:3], v2, s65, v[0:1]
	v_lshlrev_b32_e32 v2, 4, v10
	v_mov_b32_e32 v3, v215
	v_lshl_add_u64 v[0:1], v[0:1], 0, v[2:3]
	global_load_dwordx4 v[112:115], v[0:1], off offset:832
	global_load_dwordx4 v[116:119], v[0:1], off offset:864
	v_and_b32_e32 v2, 63, v8
	v_mul_u32_u24_e32 v0, 0xa00, v2
	v_bfe_u32 v2, v8, 2, 4
	v_or_b32_e32 v2, s59, v2
	v_mul_u32_u24_e32 v2, 0xa00, v2
	v_lshlrev_b32_e32 v0, 1, v0
	v_mov_b32_e32 v1, v215
	v_lshlrev_b32_e32 v2, 1, v2
	v_lshlrev_b32_e32 v4, 3, v8
	v_lshl_add_u64 v[0:1], s[16:17], 0, v[0:1]
	s_lshl_b32 s18, s64, 1
	s_mov_b32 s19, s81
	v_lshl_add_u64 v[2:3], s[16:17], 0, v[2:3]
	s_lshl_b32 s20, s60, 1
	s_mov_b32 s21, s81
	v_and_b32_e32 v11, 24, v4
	v_lshl_add_u64 v[128:129], v[0:1], 0, s[18:19]
	v_lshl_add_u64 v[2:3], v[2:3], 0, s[20:21]
	v_lshlrev_b32_e32 v4, 1, v11
	v_mov_b32_e32 v5, v215
	s_mov_b32 m0, s93
	v_lshl_add_u64 v[0:1], v[128:129], 0, s[76:77]
	v_lshl_add_u64 v[130:131], v[2:3], 0, v[4:5]
	v_mov_b32_e32 v32, v215
	v_mov_b32_e32 v33, v215
	v_mov_b32_e32 v34, v215
	v_mov_b32_e32 v35, v215
	v_mov_b32_e32 v36, v215
	v_mov_b32_e32 v37, v215
	v_mov_b32_e32 v38, v215
	v_mov_b32_e32 v39, v215
	v_mov_b32_e32 v40, v215
	v_mov_b32_e32 v41, v215
	v_mov_b32_e32 v42, v215
	v_mov_b32_e32 v43, v215
	v_mov_b32_e32 v44, v215
	v_mov_b32_e32 v45, v215
	v_mov_b32_e32 v46, v215
	v_mov_b32_e32 v47, v215
	v_readlane_b32 s2, v254, 9
	v_lshl_add_u64 v[2:3], v[130:131], 0, s[0:1]
	global_load_lds_dwordx4 v[0:1], off
	s_mov_b32 m0, s2
	s_mov_b64 s[2:3], 0x50540
	s_add_i32 s41, s93, 0x3000
	global_load_lds_dwordx4 v[2:3], off
	v_lshl_add_u64 v[0:1], v[128:129], 0, s[2:3]
	s_mov_b32 m0, s41
	s_mov_b64 s[2:3], 0xa0540
	s_add_i32 s42, s93, 0x6000
	global_load_lds_dwordx4 v[0:1], off
	v_lshl_add_u64 v[0:1], v[128:129], 0, s[2:3]
	s_mov_b32 m0, s42
	s_mov_b64 s[2:3], 0x50740
	s_add_i32 s43, s33, 0x4000
	global_load_lds_dwordx4 v[0:1], off
	v_lshl_add_u64 v[0:1], v[130:131], 0, s[2:3]
	s_mov_b32 m0, s43
	v_lshlrev_b32_e32 v132, 10, v10
	global_load_lds_dwordx4 v[0:1], off
	v_lshlrev_b32_e32 v133, 4, v9
	s_waitcnt vmcnt(2) lgkmcnt(0)
	s_barrier
	v_add3_u32 v134, 0, v132, v133
	ds_read_b128 v[0:3], v134
	ds_read_b128 v[4:7], v134 offset:512
	s_waitcnt vmcnt(2) lgkmcnt(0)
	v_mfma_f32_32x32x16_bf16 v[48:63], v[0:3], v[112:115], 0
	s_lshr_b32 s2, s40, 6
	v_mov_b32_e32 v137, 0
	s_mov_b32 s19, 1
	s_mov_b32 s21, 4
	s_mov_b32 s44, 0
	s_or_b32 s40, s2, 3
	s_mov_b64 s[2:3], 0
	v_mfma_f32_32x32x16_bf16 v[64:79], v[4:7], v[112:115], 0
	ds_read_b128 v[0:3], v134 offset:2048
	ds_read_b128 v[4:7], v134 offset:2560
	s_waitcnt lgkmcnt(0)
	s_barrier
	s_movk_i32 s45, 0x7f
	v_mov_b32_e32 v138, 0
	v_mov_b32_e32 v12, v137
	v_mov_b32_e32 v13, v137
	v_mov_b32_e32 v14, v137
	s_waitcnt lgkmcnt(1)
	v_mfma_f32_32x32x16_bf16 v[48:63], v[0:3], v[116:119], v[48:63]
	v_lshlrev_b32_e32 v2, 4, v8
	v_lshlrev_b32_e32 v0, 1, v8
	v_and_b32_e32 v2, 0xc0, v2
	v_and_b32_e32 v0, 32, v0
	v_lshl_or_b32 v2, v10, 8, v2
	v_or3_b32 v0, v2, v0, v11
	v_lshlrev_b32_e32 v1, 2, v10
	s_waitcnt lgkmcnt(0)
	v_mfma_f32_32x32x16_bf16 v[64:79], v[4:7], v[116:119], v[64:79]
	v_add_u32_e32 v135, 0, v0
	v_add_u32_e32 v0, s39, v9
	v_sub_u32_e32 v136, v0, v1
	v_mov_b32_e32 v0, 0
	v_mov_b32_e32 v1, v137
	v_mov_b32_e32 v2, v137
	v_mov_b32_e32 v3, v137
	v_mov_b32_e32 v4, v137
	v_mov_b32_e32 v5, v137
	v_mov_b32_e32 v6, v137
	v_mov_b32_e32 v7, v137
	v_mov_b32_e32 v8, v137
	v_mov_b32_e32 v9, v137
	v_mov_b32_e32 v10, v137
	v_mov_b32_e32 v11, v137
	v_mov_b32_e32 v15, v137
	v_mov_b32_e32 v16, v137
	v_mov_b32_e32 v17, v137
	v_mov_b32_e32 v18, v137
	v_mov_b32_e32 v19, v137
	v_mov_b32_e32 v20, v137
	v_mov_b32_e32 v21, v137
	v_mov_b32_e32 v22, v137
	v_mov_b32_e32 v23, v137
	v_mov_b32_e32 v24, v137
	v_mov_b32_e32 v25, v137
	v_mov_b32_e32 v26, v137
	v_mov_b32_e32 v27, v137
	v_mov_b32_e32 v28, v137
	v_mov_b32_e32 v29, v137
	v_mov_b32_e32 v30, v137
	v_mov_b32_e32 v31, v137
	v_readfirstlane_b32 s86, v128
	v_readfirstlane_b32 s87, v129
	v_readfirstlane_b32 s98, v130
	v_readfirstlane_b32 s99, v131
	s_nop 1
	v_subrev_u32_e32 v200, s86, v128
	v_subrev_u32_e32 v202, s98, v130
	s_add_u32 s86, s86, s76
	s_addc_u32 s87, s87, s77
	s_add_u32 s98, s98, s0
	s_addc_u32 s99, s99, s1
	s_branch .LBB0_732

.LBB0_732:
	s_add_i32 s4, s21, -1
	s_min_u32 s4, s4, s40
	s_mul_hi_u32 s5, s4, 0x55555556
	s_mul_i32 s5, s5, 3
	s_sub_i32 s5, s4, s5
	s_mul_i32 s4, s4, 0x28000
	s_add_i32 s46, s21, -2
	s_mulk_i32 s5, 0x3000
	s_lshl_b32 s80, s4, 1
	s_min_u32 s4, s46, s40
	s_add_i32 s48, s5, 0
	s_mul_hi_u32 s5, s4, 0x55555556
	s_mul_i32 s5, s5, 3
	s_sub_i32 s5, s4, s5
	v_add_u32_e32 v80, s80, v200
	s_mulk_i32 s5, 0x3000
	s_add_i32 m0, s48, s92
	s_add_i32 s47, s5, 0
	s_mul_i32 s4, s4, 0x50000
	s_mov_b32 s5, s81
	global_load_lds_dwordx4 v80, s[86:87]
	v_add_u32_e32 v80, s4, v202
	s_add_i32 s4, s47, s95
	s_add_i32 m0, s4, 0x1000
	s_sub_i32 s4, s45, 64
	global_load_lds_dwordx4 v80, s[98:99]
	s_cmp_le_u32 s4, s39
	s_sub_i32 s5, s4, 94
	s_cmp_gt_i32 s5, s39
	s_cbranch_scc1 .Ltsk732_d1
	s_cmp_le_u32 s4, s39
	s_cbranch_scc1 .LBB0_734
	v_cmp_lt_i32_e64 s[4:5], -1, v136
	v_cmp_lt_i32_e64 s[6:7], 31, v136
	v_cmp_lt_i32_e32 vcc, 0, v136
	v_cndmask_b32_e64 v48, v249, v48, s[4:5]
	v_cmp_lt_i32_e64 s[4:5], 32, v136
	v_cndmask_b32_e64 v64, v249, v64, s[6:7]
	v_cmp_lt_i32_e64 s[6:7], 1, v136
	v_cndmask_b32_e32 v49, v249, v49, vcc
	v_cmp_lt_i32_e32 vcc, 33, v136
	v_cndmask_b32_e64 v65, v249, v65, s[4:5]
	v_cmp_lt_i32_e64 s[4:5], 2, v136
	v_cndmask_b32_e64 v50, v249, v50, s[6:7]
	v_cmp_lt_i32_e64 s[6:7], 34, v136
	v_cndmask_b32_e32 v66, v249, v66, vcc
	v_cmp_lt_i32_e32 vcc, 7, v136
	v_cndmask_b32_e64 v51, v249, v51, s[4:5]
	v_cmp_lt_i32_e64 s[4:5], 39, v136
	v_cndmask_b32_e64 v67, v249, v67, s[6:7]
	v_cmp_lt_i32_e64 s[6:7], 8, v136
	v_cndmask_b32_e32 v52, v249, v52, vcc
	v_cmp_lt_i32_e32 vcc, 40, v136
	v_cndmask_b32_e64 v68, v249, v68, s[4:5]
	v_cmp_lt_i32_e64 s[4:5], 9, v136
	v_cndmask_b32_e64 v53, v249, v53, s[6:7]
	v_cmp_lt_i32_e64 s[6:7], 41, v136
	v_cndmask_b32_e32 v69, v249, v69, vcc
	v_cmp_lt_i32_e32 vcc, 10, v136
	v_cndmask_b32_e64 v54, v249, v54, s[4:5]
	v_cmp_lt_i32_e64 s[4:5], 42, v136
	v_cndmask_b32_e64 v70, v249, v70, s[6:7]
	v_cmp_lt_i32_e64 s[6:7], 15, v136
	v_cndmask_b32_e32 v55, v249, v55, vcc
	v_cmp_lt_i32_e32 vcc, 47, v136
	v_cndmask_b32_e64 v71, v249, v71, s[4:5]
	v_cmp_lt_i32_e64 s[4:5], 16, v136
	v_cndmask_b32_e64 v56, v249, v56, s[6:7]
	v_cmp_lt_i32_e64 s[6:7], 48, v136
	v_cndmask_b32_e32 v72, v249, v72, vcc
	v_cmp_lt_i32_e32 vcc, 17, v136
	v_cndmask_b32_e64 v57, v249, v57, s[4:5]
	v_cmp_lt_i32_e64 s[4:5], 49, v136
	v_cndmask_b32_e64 v73, v249, v73, s[6:7]
	v_cmp_lt_i32_e64 s[6:7], 18, v136
	v_cndmask_b32_e32 v58, v249, v58, vcc
	v_cmp_lt_i32_e32 vcc, 50, v136
	v_cndmask_b32_e64 v74, v249, v74, s[4:5]
	v_cmp_lt_i32_e64 s[4:5], 23, v136
	v_cndmask_b32_e64 v59, v249, v59, s[6:7]
	v_cmp_lt_i32_e64 s[6:7], 55, v136
	v_cndmask_b32_e32 v75, v249, v75, vcc
	v_cmp_lt_i32_e32 vcc, 24, v136
	v_cndmask_b32_e64 v60, v249, v60, s[4:5]
	v_cmp_lt_i32_e64 s[4:5], 56, v136
	v_cndmask_b32_e64 v76, v249, v76, s[6:7]
	v_cmp_lt_i32_e64 s[6:7], 25, v136
	v_cndmask_b32_e32 v61, v249, v61, vcc
	v_cmp_lt_i32_e32 vcc, 57, v136
	v_cndmask_b32_e64 v77, v249, v77, s[4:5]
	v_cmp_lt_i32_e64 s[4:5], 26, v136
	v_cndmask_b32_e64 v62, v249, v62, s[6:7]
	v_cmp_lt_i32_e64 s[6:7], 58, v136
	v_cndmask_b32_e32 v78, v249, v78, vcc
	s_nop 0
	v_cndmask_b32_e64 v63, v249, v63, s[4:5]
	s_nop 0
	v_cndmask_b32_e64 v79, v249, v79, s[6:7]

.Ltsk732_s2:
	s_min_u32 s4, s21, s40
	s_mul_hi_u32 s5, s4, 0x55555556
	s_mul_i32 s5, s5, 3
	s_sub_i32 s5, s4, s5
	s_mul_i32 s6, s5, 0x3000
	s_mul_i32 s4, s4, 0x50000
	s_mov_b32 s5, s81
	v_add_u32_e32 v48, s4, v200
	s_add_i32 m0, s93, s6
	s_add_i32 s4, s48, s95
	global_load_lds_dwordx4 v48, s[86:87]
	v_add_u32_e32 v48, s80, v202
	s_add_i32 m0, s4, 0x1000
	s_cmp_le_u32 s45, s39
	global_load_lds_dwordx4 v48, s[98:99]
	s_sub_i32 s5, s45, 94
	s_cmp_gt_i32 s5, s39
	s_cbranch_scc1 .Ltsk732_d2
	s_cmp_le_u32 s45, s39
	s_cbranch_scc1 .LBB0_739
	v_subrev_u32_e32 v48, 64, v136
	v_cmp_lt_i32_e64 s[4:5], -1, v48
	v_cmp_lt_i32_e64 s[6:7], 31, v48
	v_cmp_lt_i32_e32 vcc, 0, v48
	v_cndmask_b32_e64 v96, v249, v96, s[4:5]
	v_cmp_lt_i32_e64 s[4:5], 32, v48
	v_cndmask_b32_e64 v80, v249, v80, s[6:7]
	v_cmp_lt_i32_e64 s[6:7], 1, v48
	v_cndmask_b32_e32 v97, v249, v97, vcc
	v_cmp_lt_i32_e32 vcc, 33, v48
	v_cndmask_b32_e64 v81, v249, v81, s[4:5]
	v_cmp_lt_i32_e64 s[4:5], 2, v48
	v_cndmask_b32_e64 v98, v249, v98, s[6:7]
	v_cmp_lt_i32_e64 s[6:7], 34, v48
	v_cndmask_b32_e32 v82, v249, v82, vcc
	v_cmp_lt_i32_e32 vcc, 7, v48
	v_cndmask_b32_e64 v99, v249, v99, s[4:5]
	v_cmp_lt_i32_e64 s[4:5], 39, v48
	v_cndmask_b32_e64 v83, v249, v83, s[6:7]
	v_cmp_lt_i32_e64 s[6:7], 8, v48
	v_cndmask_b32_e32 v100, v249, v100, vcc
	v_cmp_lt_i32_e32 vcc, 40, v48
	v_cndmask_b32_e64 v84, v249, v84, s[4:5]
	v_cmp_lt_i32_e64 s[4:5], 9, v48
	v_cndmask_b32_e64 v101, v249, v101, s[6:7]
	v_cmp_lt_i32_e64 s[6:7], 41, v48
	v_cndmask_b32_e32 v85, v249, v85, vcc
	v_cmp_lt_i32_e32 vcc, 10, v48
	v_cndmask_b32_e64 v102, v249, v102, s[4:5]
	v_cmp_lt_i32_e64 s[4:5], 42, v48
	v_cndmask_b32_e64 v86, v249, v86, s[6:7]
	v_cmp_lt_i32_e64 s[6:7], 15, v48
	v_cndmask_b32_e32 v103, v249, v103, vcc
	v_cmp_lt_i32_e32 vcc, 47, v48
	v_cndmask_b32_e64 v87, v249, v87, s[4:5]
	v_cmp_lt_i32_e64 s[4:5], 16, v48
	v_cndmask_b32_e64 v104, v249, v104, s[6:7]
	v_cmp_lt_i32_e64 s[6:7], 48, v48
	v_cndmask_b32_e32 v88, v249, v88, vcc
	v_cmp_lt_i32_e32 vcc, 17, v48
	v_cndmask_b32_e64 v105, v249, v105, s[4:5]
	v_cmp_lt_i32_e64 s[4:5], 49, v48
	v_cndmask_b32_e64 v89, v249, v89, s[6:7]
	v_cmp_lt_i32_e64 s[6:7], 18, v48
	v_cndmask_b32_e32 v106, v249, v106, vcc
	v_cmp_lt_i32_e32 vcc, 50, v48
	v_cndmask_b32_e64 v90, v249, v90, s[4:5]
	v_cmp_lt_i32_e64 s[4:5], 23, v48
	v_cndmask_b32_e64 v107, v249, v107, s[6:7]
	v_cmp_lt_i32_e64 s[6:7], 55, v48
	v_cndmask_b32_e32 v91, v249, v91, vcc
	v_cmp_lt_i32_e32 vcc, 24, v48
	v_cndmask_b32_e64 v108, v249, v108, s[4:5]
	v_cmp_lt_i32_e64 s[4:5], 56, v48
	v_cndmask_b32_e64 v92, v249, v92, s[6:7]
	v_cmp_lt_i32_e64 s[6:7], 25, v48
	v_cndmask_b32_e32 v109, v249, v109, vcc
	v_cmp_lt_i32_e32 vcc, 57, v48
	v_cndmask_b32_e64 v93, v249, v93, s[4:5]
	v_cmp_lt_i32_e64 s[4:5], 26, v48
	v_cndmask_b32_e64 v110, v249, v110, s[6:7]
	v_cmp_lt_i32_e64 s[6:7], 58, v48
	v_cndmask_b32_e32 v94, v249, v94, vcc
	s_nop 0
	v_cndmask_b32_e64 v111, v249, v111, s[4:5]
	s_nop 0
	v_cndmask_b32_e64 v95, v249, v95, s[6:7]

; __device__ __forceinline__ int make_tid(int wave0) { int t = wave0 * 64 + (int)__builtin_amdgcn_mbcnt_hi(~0u, __builtin_amdgcn_mbcnt_lo(~0u, 0u)); asm volatile("" : "+v"(t)); return t; }
; #define LAS __attribute__((address_space(3)))
; __device__ __forceinline__ float sum32x(float v) { auto rr = __builtin_amdgcn_permlane32_swap(__float_as_uint(v), __float_as_uint(v), false, false); return __uint_as_float(rr[0]) + __uint_as_float(rr[1]); }
; #define AT_WAITBAR(N) asm volatile("s_waitcnt vmcnt(" #N ") lgkmcnt(0)\n\ts_barrier" ::: "memory")
; template <int DQK, int MODE> ...
;     ...
;     const int tid = make_tid(wave0), lane = tid & 63, r32 = lane & 31, hi = lane >> 5;
;     const int wid = wave0;
;     const int tw0 = t0 + 32 * wid, tq = tw0 + r32;
;     bf16x8 qf[NDS];
; #pragma unroll
;     for (int ds = 0; ds < NDS; ++ds) qf[ds] = *(const bf16x8*)(Qp + (size_t)tq * qs + 16 * ds + 8 * hi);
;     int kt_lo = 0; const int kt_hi = (t0 >> 6) + 3;
;     if (MODE == 1) { const int lo = t0 - 511; kt_lo = lo > 0 ? (lo >> 6) : 0; }
;     unsigned long long selm = 0ull; if (MODE == 2) selm = selp[tq];
;     const int kc0 = wid % CPR, kc1 = (8 + (wid & 3)) % CPR;
;     const bf16_t* ksrc0 = Kp + (size_t)lane * ks + kc0 * 8;
;     const bf16_t* ksrc1 = Kp + (size_t)lane * ks + kc1 * 8;
;     const bf16_t* vsrc = Vp + (size_t)(16 * (wid & 3) + (lane >> 2)) * vs + (wid >> 2) * 32 + (lane & 3) * 8;
;     ...
;     o[0] = f32x16{}; o[1] = f32x16{};
;     float m_run = 0.f, l_run = 0.f; bool init = false;
;     f32x16 negm = f32x16{}; asm volatile("" : "+v"(negm));
;     f32x16 pa0 = f32x16{}, pa1 = f32x16{}, pb0 = f32x16{}, pb1 = f32x16{};
;     bf16x8 kf[2 * NDS];
;     AT_DMAK(kt_lo); AT_DMAV(kt_lo); AT_DMAK(kt_lo + 1); AT_DMAK(kt_lo + 2); AT_DMAV(kt_lo + 1);
;     if (NKW > 1) AT_WAITBAR(3); else AT_WAITBAR(2);
;     { AT_KFRAG(kt_lo); asm volatile("s_waitcnt lgkmcnt(0)\n\ts_barrier" ::: "memory");
;       const float b_ = AT_BIAS(kt_lo); AT_QKM(pa0, pa1, AT_SPLAT(b_)); }
;     ...
;     const float lt = sum32x(l_run);
;     linv = lt > 0.f ? 1.0f / lt : 0.f;
; }
; __device__ __forceinline__ void osave(LAS unsigned char* lds, int tid, const f32x16 (&o)[2], float sc) {
;     LAS float* p = (LAS float*)(lds + OSAVE_OFF) + tid;
; #pragma unroll
;     for (int i = 0; i < 16; ++i) { p[i * 512] = o[0][i] * sc; p[(16 + i) * 512] = o[1][i] * sc; }
; }
.LBB0_741:
	v_readlane_b32 s86, v254, 37
	v_readlane_b32 s87, v254, 38
	v_mov_b32_e32 v32, v138
	s_nop 1
	v_permlane32_swap_b32_e32 v138, v32
	v_add_f32_e32 v32, v138, v32
	v_div_scale_f32 v33, s[2:3], v32, v32, 1.0
	v_rcp_f32_e32 v34, v33
	s_waitcnt vmcnt(0) lgkmcnt(0)
	s_barrier
	s_mov_b32 s19, s81
	s_mov_b32 s21, s81
	v_fma_f32 v35, -v33, v34, 1.0
	v_fmac_f32_e32 v34, v35, v34
	v_div_scale_f32 v35, vcc, 1.0, v32, 1.0
	v_mul_f32_e32 v36, v35, v34
	v_fma_f32 v37, -v33, v36, v35
	v_fmac_f32_e32 v36, v37, v34
	v_fma_f32 v33, -v33, v36, v35
	v_div_fmas_f32 v33, v33, v34, v36
	v_div_fixup_f32 v33, v33, v32, 1.0
	v_cmp_lt_f32_e32 vcc, 0, v32
	s_mov_b32 m0, s93
	v_mov_b32_e32 v34, v215
	v_cndmask_b32_e32 v32, 0, v33, vcc
	v_lshl_add_u32 v33, v191, 2, 0
	v_add_u32_e32 v132, 0x10000, v33
	v_mul_f32_e32 v0, v0, v32
	v_mul_f32_e32 v1, v1, v32
	v_mul_f32_e32 v16, v16, v32
	ds_write2st64_b32 v132, v0, v1 offset1:8
	v_mul_f32_e32 v0, v17, v32
	ds_write2st64_b32 v132, v16, v0 offset0:128 offset1:136
	v_mul_f32_e32 v0, v2, v32
	v_mul_f32_e32 v2, v3, v32
	v_mul_f32_e32 v1, v18, v32
	ds_write2st64_b32 v132, v0, v2 offset0:16 offset1:24
	v_mul_f32_e32 v0, v19, v32
	ds_write2st64_b32 v132, v1, v0 offset0:144 offset1:152
	v_mul_f32_e32 v0, v4, v32
	v_mul_f32_e32 v2, v5, v32
	v_mul_f32_e32 v1, v20, v32
	ds_write2st64_b32 v132, v0, v2 offset0:32 offset1:40
	v_mul_f32_e32 v0, v21, v32
	ds_write2st64_b32 v132, v1, v0 offset0:160 offset1:168
	v_mul_f32_e32 v0, v6, v32
	v_mul_f32_e32 v2, v7, v32
	v_mul_f32_e32 v1, v22, v32
	ds_write2st64_b32 v132, v0, v2 offset0:48 offset1:56
	v_mul_f32_e32 v0, v23, v32
	ds_write2st64_b32 v132, v1, v0 offset0:176 offset1:184
	v_mul_f32_e32 v0, v8, v32
	v_mul_f32_e32 v2, v9, v32
	v_mul_f32_e32 v1, v24, v32
	ds_write2st64_b32 v132, v0, v2 offset0:64 offset1:72
	v_mul_f32_e32 v0, v25, v32
	ds_write2st64_b32 v132, v1, v0 offset0:192 offset1:200
	v_mul_f32_e32 v0, v10, v32
	v_mul_f32_e32 v2, v11, v32
	v_mul_f32_e32 v1, v26, v32
	ds_write2st64_b32 v132, v0, v2 offset0:80 offset1:88
	v_mul_f32_e32 v0, v27, v32
	ds_write2st64_b32 v132, v1, v0 offset0:208 offset1:216
	v_mul_f32_e32 v0, v12, v32
	v_mul_f32_e32 v2, v13, v32
	v_mul_f32_e32 v1, v28, v32
	ds_write2st64_b32 v132, v0, v2 offset0:96 offset1:104
	v_mul_f32_e32 v0, v29, v32
	ds_write2st64_b32 v132, v1, v0 offset0:224 offset1:232
	v_mul_f32_e32 v0, v14, v32
	v_mul_f32_e32 v2, v15, v32
	v_mul_f32_e32 v1, v30, v32
	ds_write2st64_b32 v132, v0, v2 offset0:112 offset1:120
	v_mul_f32_e32 v0, v31, v32
	v_mov_b32_e32 v8, v246
	ds_write2st64_b32 v132, v1, v0 offset0:240 offset1:248
	v_mov_b64_e32 v[0:1], s[16:17]
	v_and_b32_e32 v9, 31, v8
	v_bfe_u32 v10, v8, 5, 1
	v_or_b32_e32 v2, s39, v9
	v_mad_u64_u32 v[0:1], s[2:3], v2, s65, v[0:1]
	v_lshlrev_b32_e32 v2, 4, v10
	v_mov_b32_e32 v3, v215
	v_lshl_add_u64 v[0:1], v[0:1], 0, v[2:3]
	global_load_dwordx4 v[112:115], v[0:1], off offset:896
	global_load_dwordx4 v[116:119], v[0:1], off offset:928
	v_and_b32_e32 v2, 63, v8
	v_mul_u32_u24_e32 v0, 0xa00, v2
	v_bfe_u32 v2, v8, 2, 4
	v_or_b32_e32 v2, s59, v2
	v_mul_u32_u24_e32 v2, 0xa00, v2
	v_lshlrev_b32_e32 v0, 1, v0
	v_mov_b32_e32 v1, v215
	v_lshlrev_b32_e32 v2, 1, v2
	v_lshlrev_b32_e32 v4, 3, v8
	v_lshl_add_u64 v[0:1], s[16:17], 0, v[0:1]
	v_lshl_add_u64 v[2:3], s[16:17], 0, v[2:3]
	v_and_b32_e32 v11, 24, v4
	v_lshl_add_u64 v[128:129], v[0:1], 0, s[18:19]
	v_lshl_add_u64 v[2:3], v[2:3], 0, s[20:21]
	v_lshlrev_b32_e32 v4, 1, v11
	v_mov_b32_e32 v5, v215
	v_lshl_add_u64 v[0:1], v[128:129], 0, s[90:91]
	v_lshl_add_u64 v[130:131], v[2:3], 0, v[4:5]
	v_mov_b32_e32 v32, v215
	v_mov_b32_e32 v33, v215
	v_mov_b32_e32 v35, v215
	v_mov_b32_e32 v36, v215
	v_mov_b32_e32 v37, v215
	v_mov_b32_e32 v38, v215
	v_mov_b32_e32 v39, v215
	v_mov_b32_e32 v40, v215
	v_mov_b32_e32 v41, v215
	v_mov_b32_e32 v42, v215
	v_mov_b32_e32 v43, v215
	v_mov_b32_e32 v44, v215
	v_mov_b32_e32 v45, v215
	v_mov_b32_e32 v46, v215
	v_mov_b32_e32 v47, v215
	v_readlane_b32 s2, v254, 9
	v_lshl_add_u64 v[2:3], v[130:131], 0, s[0:1]
	global_load_lds_dwordx4 v[0:1], off
	s_mov_b32 m0, s2
	s_mov_b64 s[2:3], 0x50580
	global_load_lds_dwordx4 v[2:3], off
	v_lshl_add_u64 v[0:1], v[128:129], 0, s[2:3]
	s_mov_b32 m0, s41
	s_mov_b64 s[2:3], 0xa0580
	global_load_lds_dwordx4 v[0:1], off
	v_lshl_add_u64 v[0:1], v[128:129], 0, s[2:3]
	s_mov_b32 m0, s42
	s_mov_b64 s[2:3], 0x50740
	global_load_lds_dwordx4 v[0:1], off
	v_lshl_add_u64 v[0:1], v[130:131], 0, s[2:3]
	s_mov_b32 m0, s43
	v_lshlrev_b32_e32 v133, 10, v10
	global_load_lds_dwordx4 v[0:1], off
	v_lshlrev_b32_e32 v134, 4, v9
	s_waitcnt vmcnt(2) lgkmcnt(0)
	s_barrier
	v_add3_u32 v135, 0, v133, v134
	ds_read_b128 v[0:3], v135
	ds_read_b128 v[4:7], v135 offset:512
	s_waitcnt vmcnt(2) lgkmcnt(0)
	v_mfma_f32_32x32x16_bf16 v[48:63], v[0:3], v[112:115], 0
	v_mov_b32_e32 v138, 0
	s_mov_b32 s16, 0
	s_mov_b32 s17, 4
	s_mov_b32 s18, 1
	s_mov_b64 s[2:3], 0
	s_movk_i32 s19, 0x7f
	v_mov_b32_e32 v139, 0
	v_mfma_f32_32x32x16_bf16 v[64:79], v[4:7], v[112:115], 0
	ds_read_b128 v[0:3], v135 offset:2048
	ds_read_b128 v[4:7], v135 offset:2560
	s_waitcnt lgkmcnt(0)
	s_barrier
	v_mov_b32_e32 v12, v138
	v_mov_b32_e32 v13, v138
	v_mov_b32_e32 v14, v138
	v_mov_b32_e32 v15, v138
	v_mov_b32_e32 v16, v138
	s_waitcnt lgkmcnt(1)
	v_mfma_f32_32x32x16_bf16 v[48:63], v[0:3], v[116:119], v[48:63]
	v_lshlrev_b32_e32 v2, 4, v8
	v_lshlrev_b32_e32 v0, 1, v8
	v_and_b32_e32 v2, 0xc0, v2
	v_and_b32_e32 v0, 32, v0
	v_lshl_or_b32 v2, v10, 8, v2
	v_or3_b32 v0, v2, v0, v11
	v_lshlrev_b32_e32 v1, 2, v10
	s_waitcnt lgkmcnt(0)
	v_mfma_f32_32x32x16_bf16 v[64:79], v[4:7], v[116:119], v[64:79]
	v_add_u32_e32 v136, 0, v0
	v_add_u32_e32 v0, s39, v9
	v_sub_u32_e32 v137, v0, v1
	v_mov_b32_e32 v0, 0
	v_mov_b32_e32 v1, v138
	v_mov_b32_e32 v2, v138
	v_mov_b32_e32 v3, v138
	v_mov_b32_e32 v4, v138
	v_mov_b32_e32 v5, v138
	v_mov_b32_e32 v6, v138
	v_mov_b32_e32 v7, v138
	v_mov_b32_e32 v8, v138
	v_mov_b32_e32 v9, v138
	v_mov_b32_e32 v10, v138
	v_mov_b32_e32 v11, v138
	v_mov_b32_e32 v17, v138
	v_mov_b32_e32 v18, v138
	v_mov_b32_e32 v19, v138
	v_mov_b32_e32 v20, v138
	v_mov_b32_e32 v21, v138
	v_mov_b32_e32 v22, v138
	v_mov_b32_e32 v23, v138
	v_mov_b32_e32 v24, v138
	v_mov_b32_e32 v25, v138
	v_mov_b32_e32 v26, v138
	v_mov_b32_e32 v27, v138
	v_mov_b32_e32 v28, v138
	v_mov_b32_e32 v29, v138
	v_mov_b32_e32 v30, v138
	v_mov_b32_e32 v31, v138
	v_readfirstlane_b32 s86, v128
	v_readfirstlane_b32 s87, v129
	v_readfirstlane_b32 s98, v130
	v_readfirstlane_b32 s99, v131
	s_nop 1
	v_subrev_u32_e32 v200, s86, v128
	v_subrev_u32_e32 v202, s98, v130
	s_add_u32 s86, s86, s90
	s_addc_u32 s87, s87, s91
	s_add_u32 s98, s98, s0
	s_addc_u32 s99, s99, s1
	s_branch .LBB0_744

.LBB0_744:
	s_add_i32 s4, s17, -1
	s_min_u32 s4, s4, s40
	s_mul_hi_u32 s5, s4, 0x55555556
	s_mul_i32 s5, s5, 3
	s_sub_i32 s5, s4, s5
	s_mul_i32 s4, s4, 0x28000
	s_add_i32 s20, s17, -2
	s_mulk_i32 s5, 0x3000
	s_lshl_b32 s80, s4, 1
	s_min_u32 s4, s20, s40
	s_add_i32 s41, s5, 0
	s_mul_hi_u32 s5, s4, 0x55555556
	s_mul_i32 s5, s5, 3
	s_sub_i32 s5, s4, s5
	v_add_u32_e32 v80, s80, v200
	s_mulk_i32 s5, 0x3000
	s_add_i32 m0, s41, s92
	s_add_i32 s21, s5, 0
	s_mul_i32 s4, s4, 0x50000
	s_mov_b32 s5, s81
	global_load_lds_dwordx4 v80, s[86:87]
	v_add_u32_e32 v80, s4, v202
	s_add_i32 s4, s21, s95
	s_add_i32 m0, s4, 0x1000
	s_sub_i32 s4, s19, 64
	global_load_lds_dwordx4 v80, s[98:99]
	s_cmp_le_u32 s4, s39
	s_sub_i32 s5, s4, 94
	s_cmp_gt_i32 s5, s39
	s_cbranch_scc1 .Ltsk744_d1
	s_cmp_le_u32 s4, s39
	s_cbranch_scc1 .LBB0_746
	v_cmp_lt_i32_e64 s[4:5], -1, v137
	v_cmp_lt_i32_e64 s[6:7], 31, v137
	v_cmp_lt_i32_e32 vcc, 0, v137
	v_cndmask_b32_e64 v48, v249, v48, s[4:5]
	v_cmp_lt_i32_e64 s[4:5], 32, v137
	v_cndmask_b32_e64 v64, v249, v64, s[6:7]
	v_cmp_lt_i32_e64 s[6:7], 1, v137
	v_cndmask_b32_e32 v49, v249, v49, vcc
	v_cmp_lt_i32_e32 vcc, 33, v137
	v_cndmask_b32_e64 v65, v249, v65, s[4:5]
	v_cmp_lt_i32_e64 s[4:5], 2, v137
	v_cndmask_b32_e64 v50, v249, v50, s[6:7]
	v_cmp_lt_i32_e64 s[6:7], 34, v137
	v_cndmask_b32_e32 v66, v249, v66, vcc
	v_cmp_lt_i32_e32 vcc, 7, v137
	v_cndmask_b32_e64 v51, v249, v51, s[4:5]
	v_cmp_lt_i32_e64 s[4:5], 39, v137
	v_cndmask_b32_e64 v67, v249, v67, s[6:7]
	v_cmp_lt_i32_e64 s[6:7], 8, v137
	v_cndmask_b32_e32 v52, v249, v52, vcc
	v_cmp_lt_i32_e32 vcc, 40, v137
	v_cndmask_b32_e64 v68, v249, v68, s[4:5]
	v_cmp_lt_i32_e64 s[4:5], 9, v137
	v_cndmask_b32_e64 v53, v249, v53, s[6:7]
	v_cmp_lt_i32_e64 s[6:7], 41, v137
	v_cndmask_b32_e32 v69, v249, v69, vcc
	v_cmp_lt_i32_e32 vcc, 10, v137
	v_cndmask_b32_e64 v54, v249, v54, s[4:5]
	v_cmp_lt_i32_e64 s[4:5], 42, v137
	v_cndmask_b32_e64 v70, v249, v70, s[6:7]
	v_cmp_lt_i32_e64 s[6:7], 15, v137
	v_cndmask_b32_e32 v55, v249, v55, vcc
	v_cmp_lt_i32_e32 vcc, 47, v137
	v_cndmask_b32_e64 v71, v249, v71, s[4:5]
	v_cmp_lt_i32_e64 s[4:5], 16, v137
	v_cndmask_b32_e64 v56, v249, v56, s[6:7]
	v_cmp_lt_i32_e64 s[6:7], 48, v137
	v_cndmask_b32_e32 v72, v249, v72, vcc
	v_cmp_lt_i32_e32 vcc, 17, v137
	v_cndmask_b32_e64 v57, v249, v57, s[4:5]
	v_cmp_lt_i32_e64 s[4:5], 49, v137
	v_cndmask_b32_e64 v73, v249, v73, s[6:7]
	v_cmp_lt_i32_e64 s[6:7], 18, v137
	v_cndmask_b32_e32 v58, v249, v58, vcc
	v_cmp_lt_i32_e32 vcc, 50, v137
	v_cndmask_b32_e64 v74, v249, v74, s[4:5]
	v_cmp_lt_i32_e64 s[4:5], 23, v137
	v_cndmask_b32_e64 v59, v249, v59, s[6:7]
	v_cmp_lt_i32_e64 s[6:7], 55, v137
	v_cndmask_b32_e32 v75, v249, v75, vcc
	v_cmp_lt_i32_e32 vcc, 24, v137
	v_cndmask_b32_e64 v60, v249, v60, s[4:5]
	v_cmp_lt_i32_e64 s[4:5], 56, v137
	v_cndmask_b32_e64 v76, v249, v76, s[6:7]
	v_cmp_lt_i32_e64 s[6:7], 25, v137
	v_cndmask_b32_e32 v61, v249, v61, vcc
	v_cmp_lt_i32_e32 vcc, 57, v137
	v_cndmask_b32_e64 v77, v249, v77, s[4:5]
	v_cmp_lt_i32_e64 s[4:5], 26, v137
	v_cndmask_b32_e64 v62, v249, v62, s[6:7]
	v_cmp_lt_i32_e64 s[6:7], 58, v137
	v_cndmask_b32_e32 v78, v249, v78, vcc
	s_nop 0
	v_cndmask_b32_e64 v63, v249, v63, s[4:5]
	s_nop 0
	v_cndmask_b32_e64 v79, v249, v79, s[6:7]

.Ltsk744_s2:
	s_min_u32 s4, s17, s40
	s_mul_hi_u32 s5, s4, 0x55555556
	s_mul_i32 s5, s5, 3
	s_sub_i32 s5, s4, s5
	s_mul_i32 s6, s5, 0x3000
	s_mul_i32 s4, s4, 0x50000
	s_mov_b32 s5, s81
	v_add_u32_e32 v48, s4, v200
	s_add_i32 m0, s93, s6
	s_add_i32 s4, s41, s95
	global_load_lds_dwordx4 v48, s[86:87]
	v_add_u32_e32 v48, s80, v202
	s_add_i32 m0, s4, 0x1000
	s_cmp_le_u32 s19, s39
	global_load_lds_dwordx4 v48, s[98:99]
	s_sub_i32 s5, s19, 94
	s_cmp_gt_i32 s5, s39
	s_cbranch_scc1 .Ltsk744_d2
	s_cmp_le_u32 s19, s39
	s_cbranch_scc1 .LBB0_751
	v_subrev_u32_e32 v48, 64, v137
	v_cmp_lt_i32_e64 s[4:5], -1, v48
	v_cmp_lt_i32_e64 s[6:7], 31, v48
	v_cmp_lt_i32_e32 vcc, 0, v48
	v_cndmask_b32_e64 v96, v249, v96, s[4:5]
	v_cmp_lt_i32_e64 s[4:5], 32, v48
	v_cndmask_b32_e64 v80, v249, v80, s[6:7]
	v_cmp_lt_i32_e64 s[6:7], 1, v48
	v_cndmask_b32_e32 v97, v249, v97, vcc
	v_cmp_lt_i32_e32 vcc, 33, v48
	v_cndmask_b32_e64 v81, v249, v81, s[4:5]
	v_cmp_lt_i32_e64 s[4:5], 2, v48
	v_cndmask_b32_e64 v98, v249, v98, s[6:7]
	v_cmp_lt_i32_e64 s[6:7], 34, v48
	v_cndmask_b32_e32 v82, v249, v82, vcc
	v_cmp_lt_i32_e32 vcc, 7, v48
	v_cndmask_b32_e64 v99, v249, v99, s[4:5]
	v_cmp_lt_i32_e64 s[4:5], 39, v48
	v_cndmask_b32_e64 v83, v249, v83, s[6:7]
	v_cmp_lt_i32_e64 s[6:7], 8, v48
	v_cndmask_b32_e32 v100, v249, v100, vcc
	v_cmp_lt_i32_e32 vcc, 40, v48
	v_cndmask_b32_e64 v84, v249, v84, s[4:5]
	v_cmp_lt_i32_e64 s[4:5], 9, v48
	v_cndmask_b32_e64 v101, v249, v101, s[6:7]
	v_cmp_lt_i32_e64 s[6:7], 41, v48
	v_cndmask_b32_e32 v85, v249, v85, vcc
	v_cmp_lt_i32_e32 vcc, 10, v48
	v_cndmask_b32_e64 v102, v249, v102, s[4:5]
	v_cmp_lt_i32_e64 s[4:5], 42, v48
	v_cndmask_b32_e64 v86, v249, v86, s[6:7]
	v_cmp_lt_i32_e64 s[6:7], 15, v48
	v_cndmask_b32_e32 v103, v249, v103, vcc
	v_cmp_lt_i32_e32 vcc, 47, v48
	v_cndmask_b32_e64 v87, v249, v87, s[4:5]
	v_cmp_lt_i32_e64 s[4:5], 16, v48
	v_cndmask_b32_e64 v104, v249, v104, s[6:7]
	v_cmp_lt_i32_e64 s[6:7], 48, v48
	v_cndmask_b32_e32 v88, v249, v88, vcc
	v_cmp_lt_i32_e32 vcc, 17, v48
	v_cndmask_b32_e64 v105, v249, v105, s[4:5]
	v_cmp_lt_i32_e64 s[4:5], 49, v48
	v_cndmask_b32_e64 v89, v249, v89, s[6:7]
	v_cmp_lt_i32_e64 s[6:7], 18, v48
	v_cndmask_b32_e32 v106, v249, v106, vcc
	v_cmp_lt_i32_e32 vcc, 50, v48
	v_cndmask_b32_e64 v90, v249, v90, s[4:5]
	v_cmp_lt_i32_e64 s[4:5], 23, v48
	v_cndmask_b32_e64 v107, v249, v107, s[6:7]
	v_cmp_lt_i32_e64 s[6:7], 55, v48
	v_cndmask_b32_e32 v91, v249, v91, vcc
	v_cmp_lt_i32_e32 vcc, 24, v48
	v_cndmask_b32_e64 v108, v249, v108, s[4:5]
	v_cmp_lt_i32_e64 s[4:5], 56, v48
	v_cndmask_b32_e64 v92, v249, v92, s[6:7]
	v_cmp_lt_i32_e64 s[6:7], 25, v48
	v_cndmask_b32_e32 v109, v249, v109, vcc
	v_cmp_lt_i32_e32 vcc, 57, v48
	v_cndmask_b32_e64 v93, v249, v93, s[4:5]
	v_cmp_lt_i32_e64 s[4:5], 26, v48
	v_cndmask_b32_e64 v110, v249, v110, s[6:7]
	v_cmp_lt_i32_e64 s[6:7], 58, v48
	v_cndmask_b32_e32 v94, v249, v94, vcc
	s_nop 0
	v_cndmask_b32_e64 v111, v249, v111, s[4:5]
	s_nop 0
	v_cndmask_b32_e64 v95, v249, v95, s[6:7]
